# P8 and P9 GEMM k-loops also converted to 3-stage LDS-DMA pipeline
# speedup vs baseline: 1.0366x; 1.0150x over previous
; DEVI int TID() { int t = threadIdx.x; asm volatile("" : "+v"(t)); return t; }
;   const int tid = TID(), lane = tid & 63, wave = tid >> 6;
;   const int l15 = lane & 15, quad = lane >> 4;
;   const int wm = wave >> 1, wn = wave & 1;
;   const int TM = KS > 0 ? 128 : NTOK / 256;
;   const int total = TM * TN + (KS > 0 ? TN * KS : 0);
;   const int nkfull = K / 32;
;   const int ldrow = tid >> 2, ldp = tid & 3;
;   const int lsw = ((ldp ^ ((ldrow >> 2) & 3)) * 16);
;   const int rsw = ((quad ^ ((l15 >> 2) & 3)) * 16);
;   const int nfullp = TN >> 3;
;     ...
;     const u16* Ag = A + (size_t)(m0 + ldrow) * K + ldp * 8 + kt0 * 32;
;     const u16* Bg = Bt + (size_t)(n0 + ldrow) * K + ldp * 8 + kt0 * 32;
.LBB0_1455:
	s_or_b64 exec, exec, s[2:3]
	v_mov_b32_e32 v6, v1
	s_barrier
	v_readlane_b32 s2, v251, 56
	v_lshrrev_b32_e32 v4, 4, v6
	v_lshrrev_b32_e32 v9, 2, v6
	v_xor_b32_e32 v4, v4, v9
	v_lshlrev_b32_e32 v5, 4, v6
	v_lshlrev_b32_e32 v4, 4, v4
	v_bitop3_b32 v8, v5, 48, v6 bitop3:0x48
	v_and_b32_e32 v10, 48, v4
	v_and_b32_e32 v4, 48, v5
	v_mov_b32_e32 v5, v2
	v_readlane_b32 s3, v251, 57
	v_ashrrev_i32_e32 v3, 2, v6
	v_bfe_u32 v7, v6, 6, 1
	v_lshl_add_u64 v[132:133], s[2:3], 0, v[4:5]
	v_readlane_b32 s2, v252, 34
	v_readlane_b32 s3, v252, 35
	v_add_u32_e32 v8, 0, v8
	v_lshlrev_b32_e32 v144, 12, v7
	v_lshl_add_u64 v[134:135], s[2:3], 0, v[4:5]
	v_lshlrev_b32_e32 v4, 6, v3
	v_and_b32_e32 v5, 12, v9
	v_lshl_or_b32 v143, v7, 6, v5
	v_lshlrev_b32_e32 v5, 6, v6
	v_add_u32_e32 v147, 0, v10
	v_add_u32_e32 v148, v8, v4
	v_and_b32_e32 v4, 3, v6
	v_readlane_b32 s2, v251, 1
	v_and_b32_e32 v145, 0x3c0, v5
	v_and_b32_e32 v146, 0xffffe3c0, v5
	v_add_u32_e32 v7, v147, v144
	v_lshlrev_b32_e32 v4, 4, v4
	v_mov_b32_e32 v5, v2
	v_readlane_b32 s3, v251, 2
	v_and_b32_e32 v142, 0xffffff8f, v6
	v_add_u32_e32 v149, v7, v145
	v_lshl_add_u64 v[136:137], s[2:3], 0, v[4:5]
	s_mov_b32 s2, 0
	s_mov_b32 s4, 0
	v_writelane_b32 v255, s20, 41
	v_writelane_b32 v255, s21, 42
	v_writelane_b32 v255, s22, 43
	v_writelane_b32 v255, s23, 44
	v_lshrrev_b32_e32 v4, 6, v1
	v_lshrrev_b32_e32 v5, 4, v1
	v_xor_b32_e32 v5, v5, v1
	v_readfirstlane_b32 s20, v4
	v_and_b32_e32 v5, 3, v5
	v_and_b32_e32 v4, 3, v1
	v_sub_u32_e32 v4, v5, v4
	v_lshlrev_b32_e32 v4, 4, v4
	v_ashrrev_i32_e32 v5, 31, v4
	s_lshl_b32 s20, s20, 10
	v_lshl_add_u64 v[132:133], v[132:133], 0, v[4:5]
	v_lshl_add_u64 v[134:135], v[134:135], 0, v[4:5]
	v_lshl_add_u64 v[136:137], v[136:137], 0, v[4:5]
	s_branch .LBB0_1457

;     ...
;   for (int rnd = 0; rnd * nb < total; ++rnd) {
;     const int id = rnd * nb + (bid & 7) * (nb >> 3) + (bid >> 3);
;     if (id >= total) continue;
;     int tm, tn;
;     int kt0 = 0, nk = nkfull;
;     bool split = false;
;     if (id >= TM * TN) {
;       const int piece = id - TM * TN;
;       tn = piece / KS;
;       const int ks = piece - tn * KS;
;       tm = 128;
;       nk = nkfull / KS;
;       kt0 = ks * nk;
;       split = true;
;     } else {
;       const int pan = id / (TM * 8);
;       if (pan < nfullp) {
;         const int r = id - pan * (TM * 8);
;         tm = r >> 3; tn = pan * 8 + (r & 7);
;       } else {
;         const int pw = TN - nfullp * 8;
;         const int r = id - nfullp * (TM * 8);
;         tm = r / pw; tn = nfullp * 8 + r % pw;
;       }
;     }
;     const int m0 = tm * 256, n0 = tn * 128;
;     f32x4 acc[8][4];
; #pragma unroll
;     for (int i = 0; i < 8; ++i)
; #pragma unroll
;       for (int j = 0; j < 4; ++j) acc[i][j] = f32x4{0.f, 0.f, 0.f, 0.f};
;     u32x4 ra[4], rb[2];
;     const u16* Ag = A + (size_t)(m0 + ldrow) * K + ldp * 8 + kt0 * 32;
;     const u16* Bg = Bt + (size_t)(n0 + ldrow) * K + ldp * 8 + kt0 * 32;
; #pragma unroll
;     for (int i = 0; i < 4; ++i) ra[i] = *(const u32x4*)(Ag + (size_t)(i * 64) * K);
; #pragma unroll
;     for (int i = 0; i < 2; ++i) rb[i] = *(const u32x4*)(Bg + (size_t)(i * 64) * K);
;     __syncthreads();
; #pragma unroll
;     for (int i = 0; i < 4; ++i) *(u32x4*)(smem + (ldrow + i * 64) * 64 + lsw) = ra[i];
; #pragma unroll
;     for (int i = 0; i < 2; ++i) *(u32x4*)(smem + 16384 + (ldrow + i * 64) * 64 + lsw) = rb[i];
;     __syncthreads();
.LBB0_1457:
	v_readlane_b32 s3, v254, 13
	s_add_i32 s2, s2, s3
	s_cmpk_gt_i32 s2, 0x203f
	s_cbranch_scc1 .LBB0_1456
	s_mul_hi_i32 s3, s2, 0xfe03f81
	s_lshr_b32 s5, s3, 31
	s_ashr_i32 s3, s3, 6
	s_add_i32 s3, s3, s5
	s_mul_i32 s5, s3, 0xfffffbf8
	s_add_i32 s5, s5, s2
	s_lshl_b32 s5, s5, 5
	s_and_b32 s5, s5, 0xffffff00
	s_lshl_b32 s2, s2, 7
	s_and_b32 s2, s2, 0x380
	s_lshl_b32 s3, s3, 10
	v_add_u32_e32 v4, s5, v3
	s_or_b32 s6, s3, s2
	v_ashrrev_i32_e32 v5, 31, v4
	s_waitcnt vmcnt(3)
	v_lshlrev_b64 v[64:65], 12, v[4:5]
	v_add_u32_e32 v6, s6, v3
	v_lshl_add_u64 v[4:5], v[132:133], 0, v[64:65]
	v_ashrrev_i32_e32 v7, 31, v6
	v_lshlrev_b64 v[66:67], 12, v[6:7]
	v_add_co_u32_e32 v6, vcc, s10, v4
	s_mov_b32 s2, 0x80000
	s_nop 0
	v_addc_co_u32_e32 v7, vcc, 0, v5, vcc
	s_barrier
	s_mov_b32 m0, s20
	s_nop 0
	global_load_lds_dwordx4 v[4:5], off
	s_add_u32 m0, s20, 0x5fc0
	s_nop 0
	global_load_lds_dwordx4 v[4:5], off offset:64
	s_add_u32 m0, s20, 0x1000
	s_nop 0
	global_load_lds_dwordx4 v[6:7], off
	s_add_u32 m0, s20, 0x6fc0
	s_nop 0
	global_load_lds_dwordx4 v[6:7], off offset:64
	v_add_co_u32_e32 v6, vcc, s2, v4
	v_lshl_add_u64 v[8:9], v[134:135], 0, v[66:67]
	s_nop 0
	v_addc_co_u32_e32 v7, vcc, 0, v5, vcc
	v_add_co_u32_e32 v10, vcc, s10, v8
	s_mov_b32 s2, 0xc0000
	s_nop 0
	v_addc_co_u32_e32 v11, vcc, 0, v9, vcc
	v_add_co_u32_e32 v4, vcc, s2, v4
	s_add_u32 m0, s20, 0x4000
	s_nop 0
	global_load_lds_dwordx4 v[8:9], off
	s_add_u32 m0, s20, 0x9fc0
	s_nop 0
	global_load_lds_dwordx4 v[8:9], off offset:64
	s_add_u32 m0, s20, 0x5000
	s_nop 0
	global_load_lds_dwordx4 v[10:11], off
	s_add_u32 m0, s20, 0xafc0
	s_nop 0
	global_load_lds_dwordx4 v[10:11], off offset:64
	v_addc_co_u32_e32 v5, vcc, 0, v5, vcc
	s_add_u32 m0, s20, 0x2000
	s_nop 0
	global_load_lds_dwordx4 v[6:7], off
	s_add_u32 m0, s20, 0x7fc0
	s_nop 0
	global_load_lds_dwordx4 v[6:7], off offset:64
	s_add_u32 m0, s20, 0x3000
	s_nop 0
	global_load_lds_dwordx4 v[4:5], off
	s_add_u32 m0, s20, 0x8fc0
	s_nop 0
	global_load_lds_dwordx4 v[4:5], off offset:64
	v_mov_b32_e32 v4, 0
	s_mov_b32 s7, 0
	s_mov_b64 s[2:3], 0x80
	v_mov_b32_e32 v5, v4
	v_mov_b32_e32 v6, v4
	v_mov_b32_e32 v7, v4
	v_mov_b32_e32 v8, v4
	v_mov_b32_e32 v9, v4
	v_mov_b32_e32 v10, v4
	v_mov_b32_e32 v11, v4
	v_mov_b32_e32 v12, v4
	v_mov_b32_e32 v13, v4
	v_mov_b32_e32 v14, v4
	v_mov_b32_e32 v15, v4
	v_mov_b32_e32 v16, v4
	v_mov_b32_e32 v17, v4
	v_mov_b32_e32 v18, v4
	v_mov_b32_e32 v19, v4
	v_mov_b32_e32 v20, v4
	v_mov_b32_e32 v21, v4
	v_mov_b32_e32 v22, v4
	v_mov_b32_e32 v23, v4
	v_mov_b32_e32 v24, v4
	v_mov_b32_e32 v25, v4
	v_mov_b32_e32 v26, v4
	v_mov_b32_e32 v27, v4
	v_mov_b32_e32 v28, v4
	v_mov_b32_e32 v29, v4
	v_mov_b32_e32 v30, v4
	v_mov_b32_e32 v31, v4
	v_mov_b32_e32 v32, v4
	v_mov_b32_e32 v33, v4
	v_mov_b32_e32 v34, v4
	v_mov_b32_e32 v35, v4
	v_mov_b32_e32 v36, v4
	v_mov_b32_e32 v37, v4
	v_mov_b32_e32 v38, v4
	v_lshl_add_u64 v[138:139], v[136:137], 0, v[66:67]
	v_lshl_add_u64 v[140:141], v[136:137], 0, v[64:65]
	v_mov_b32_e32 v39, v4
	v_mov_b32_e32 v64, v4
	v_mov_b32_e32 v65, v4
	v_mov_b32_e32 v66, v4
	v_mov_b32_e32 v67, v4
	v_mov_b32_e32 v68, v4
	v_mov_b32_e32 v69, v4
	v_mov_b32_e32 v70, v4
	v_mov_b32_e32 v71, v4
	v_mov_b32_e32 v72, v4
	v_mov_b32_e32 v73, v4
	v_mov_b32_e32 v74, v4
	v_mov_b32_e32 v75, v4
	v_mov_b32_e32 v76, v4
	v_mov_b32_e32 v77, v4
	v_mov_b32_e32 v40, v4
	v_mov_b32_e32 v41, v4
	v_mov_b32_e32 v42, v4
	v_mov_b32_e32 v43, v4
	v_mov_b32_e32 v44, v4
	v_mov_b32_e32 v45, v4
	v_mov_b32_e32 v46, v4
	v_mov_b32_e32 v47, v4
	v_mov_b32_e32 v48, v4
	v_mov_b32_e32 v49, v4
	v_mov_b32_e32 v50, v4
	v_mov_b32_e32 v51, v4
	v_mov_b32_e32 v52, v4
	v_mov_b32_e32 v53, v4
	v_mov_b32_e32 v54, v4
	v_mov_b32_e32 v55, v4
	v_mov_b32_e32 v56, v4
	v_mov_b32_e32 v57, v4
	v_mov_b32_e32 v58, v4
	v_mov_b32_e32 v59, v4
	v_mov_b32_e32 v60, v4
	v_mov_b32_e32 v61, v4
	v_mov_b32_e32 v62, v4
	v_mov_b32_e32 v63, v4
	v_mov_b32_e32 v78, v4
	v_mov_b32_e32 v79, v4
	v_mov_b32_e32 v80, v4
	v_mov_b32_e32 v81, v4
	v_mov_b32_e32 v82, v4
	v_mov_b32_e32 v83, v4
	v_mov_b32_e32 v84, v4
	v_mov_b32_e32 v85, v4
	v_mov_b32_e32 v86, v4
	v_mov_b32_e32 v87, v4
	v_mov_b32_e32 v88, v4
	v_mov_b32_e32 v89, v4
	v_mov_b32_e32 v90, v4
	v_mov_b32_e32 v91, v4
	v_mov_b32_e32 v92, v4
	v_mov_b32_e32 v93, v4
	v_mov_b32_e32 v94, v4
	v_mov_b32_e32 v95, v4
	v_mov_b32_e32 v96, v4
	v_mov_b32_e32 v97, v4
	v_mov_b32_e32 v98, v4
	v_mov_b32_e32 v99, v4
	v_mov_b32_e32 v100, v4
	v_mov_b32_e32 v101, v4
	v_mov_b32_e32 v102, v4
	v_mov_b32_e32 v103, v4
	v_mov_b32_e32 v104, v4
	v_mov_b32_e32 v105, v4
	v_mov_b32_e32 v106, v4
	v_mov_b32_e32 v107, v4
	v_mov_b32_e32 v108, v4
	v_mov_b32_e32 v109, v4
	v_mov_b32_e32 v110, v4
	v_mov_b32_e32 v111, v4
	v_mov_b32_e32 v112, v4
	v_mov_b32_e32 v113, v4
	v_mov_b32_e32 v114, v4
	v_mov_b32_e32 v115, v4
	v_mov_b32_e32 v116, v4
	v_mov_b32_e32 v117, v4
	v_mov_b32_e32 v118, v4
	v_mov_b32_e32 v119, v4
	v_mov_b32_e32 v120, v4
	v_mov_b32_e32 v121, v4
	v_mov_b32_e32 v122, v4
	v_mov_b32_e32 v123, v4
	v_mov_b32_e32 v124, v4
	v_mov_b32_e32 v125, v4
	v_mov_b32_e32 v126, v4
	v_mov_b32_e32 v127, v4
	v_mov_b32_e32 v128, v4
	v_mov_b32_e32 v129, v4
	v_mov_b32_e32 v130, v4
	v_mov_b32_e32 v131, v4
	s_mov_b32 s12, 0x24c0000
	s_mov_b32 s13, 0x2500000
	s_mov_b32 s14, 0x2540000
	s_mov_b32 s21, 0
	s_mov_b32 s22, 0xc000
	s_waitcnt vmcnt(0) lgkmcnt(0)
	s_barrier
;     ...
;     for (int kt = 0; kt < nk; ++kt) {
;       const int buf = kt & 1;
;       if (kt + 1 < nk) {
; #pragma unroll
;         for (int i = 0; i < 4; ++i) ra[i] = *(const u32x4*)(Ag + (size_t)(i * 64) * K + (kt + 1) * 32);
; #pragma unroll
;         for (int i = 0; i < 2; ++i) rb[i] = *(const u32x4*)(Bg + (size_t)(i * 64) * K + (kt + 1) * 32);
;       }
;       const char* As = smem + buf * 24576;
;       const char* Bs = As + 16384;
;       bf16x8 bfr[4];
; #pragma unroll
;       for (int j = 0; j < 4; ++j) bfr[j] = *(const bf16x8*)(Bs + (wn * 64 + j * 16 + l15) * 64 + rsw);
;       bf16x8 afr[8];
; #pragma unroll
;       for (int i = 0; i < 8; ++i) afr[i] = *(const bf16x8*)(As + (wm * 128 + i * 16 + l15) * 64 + rsw);
;       __builtin_amdgcn_s_setprio(1);
; #pragma unroll
;       for (int i = 0; i < 8; ++i) {
; #pragma unroll
;         for (int j = 0; j < 4; ++j) acc[i][j] = __builtin_amdgcn_mfma_f32_16x16x32_bf16(bfr[j], afr[i], acc[i][j], 0, 0, 0);
;       }
;       __builtin_amdgcn_s_setprio(0);
;       if (kt + 1 < nk) {
;         char* Aw = smem + (buf ^ 1) * 24576;
;         char* Bw = Aw + 16384;
; #pragma unroll
;         for (int i = 0; i < 4; ++i) *(u32x4*)(Aw + (ldrow + i * 64) * 64 + lsw) = ra[i];
; #pragma unroll
;         for (int i = 0; i < 2; ++i) *(u32x4*)(Bw + (ldrow + i * 64) * 64 + lsw) = rb[i];
;       }
;       __syncthreads();
;     }
.LBB0_1459:
	v_lshl_add_u64 v[150:151], v[140:141], 0, s[2:3]
	v_add_co_u32_e32 v154, vcc, s11, v150
	v_lshl_add_u64 v[152:153], v[138:139], 0, s[2:3]
	s_add_u32 s23, s22, s20
	v_addc_co_u32_e32 v155, vcc, 0, v151, vcc
	v_add_co_u32_e32 v156, vcc, s12, v150
	s_mov_b32 s8, 0x3de33000
	s_nop 0
	v_addc_co_u32_e32 v157, vcc, 0, v151, vcc
	v_add_co_u32_e32 v158, vcc, s13, v150
	s_mov_b32 m0, s23
	s_nop 0
	v_addc_co_u32_e32 v159, vcc, 0, v151, vcc
	v_add_co_u32_e32 v162, vcc, s14, v150
	s_nop 1
	v_addc_co_u32_e32 v163, vcc, 0, v151, vcc
	v_add_co_u32_e32 v166, vcc, s8, v152
	s_mov_b32 s8, 0x3de73000
	s_nop 0
	v_addc_co_u32_e32 v167, vcc, 0, v153, vcc
	v_add_co_u32_e32 v170, vcc, s8, v152
	s_nop 1
	v_addc_co_u32_e32 v171, vcc, 0, v153, vcc
	global_load_lds_dwordx4 v[154:155], off
	s_add_u32 m0, s23, 0x1000
	s_nop 0
	global_load_lds_dwordx4 v[156:157], off
	s_add_u32 m0, s23, 0x2000
	s_nop 0
	global_load_lds_dwordx4 v[158:159], off
	s_add_u32 m0, s23, 0x3000
	s_nop 0
	global_load_lds_dwordx4 v[162:163], off
	s_add_u32 m0, s23, 0x4000
	s_nop 0
	global_load_lds_dwordx4 v[166:167], off
	s_add_u32 m0, s23, 0x5000
	s_nop 0
	global_load_lds_dwordx4 v[170:171], off
	v_add_u32_e32 v174, s21, v147
	v_add3_u32 v186, v174, v144, v145
	v_add_u32_e32 v229, v174, v146
	ds_read_b128 v[174:177], v186 offset:16384
	ds_read_b128 v[178:181], v186 offset:17408
	ds_read_b128 v[182:185], v186 offset:18432
	ds_read_b128 v[186:189], v186 offset:19456
	ds_read_b128 v[190:193], v229
	ds_read_b128 v[194:197], v229 offset:1024
	ds_read_b128 v[198:201], v229 offset:2048
	ds_read_b128 v[210:213], v229 offset:3072
	ds_read_b128 v[220:223], v229 offset:4096
	ds_read_b128 v[224:227], v229 offset:5120
	ds_read_b128 v[230:233], v229 offset:6144
	ds_read_b128 v[234:237], v229 offset:7168
	s_add_i32 s7, s7, 1
	s_setprio 1
	s_waitcnt lgkmcnt(7)
	v_mfma_f32_16x16x32_bf16 v[128:131], v[174:177], v[190:193], v[128:131]
	v_mfma_f32_16x16x32_bf16 v[124:127], v[178:181], v[190:193], v[124:127]
	v_mfma_f32_16x16x32_bf16 v[120:123], v[182:185], v[190:193], v[120:123]
	v_mfma_f32_16x16x32_bf16 v[116:119], v[186:189], v[190:193], v[116:119]
	s_waitcnt lgkmcnt(6)
	v_mfma_f32_16x16x32_bf16 v[112:115], v[174:177], v[194:197], v[112:115]
	v_mfma_f32_16x16x32_bf16 v[108:111], v[178:181], v[194:197], v[108:111]
	v_mfma_f32_16x16x32_bf16 v[104:107], v[182:185], v[194:197], v[104:107]
	v_mfma_f32_16x16x32_bf16 v[100:103], v[186:189], v[194:197], v[100:103]
	s_waitcnt lgkmcnt(5)
	v_mfma_f32_16x16x32_bf16 v[96:99], v[174:177], v[198:201], v[96:99]
	v_mfma_f32_16x16x32_bf16 v[92:95], v[178:181], v[198:201], v[92:95]
	v_mfma_f32_16x16x32_bf16 v[88:91], v[182:185], v[198:201], v[88:91]
	v_mfma_f32_16x16x32_bf16 v[84:87], v[186:189], v[198:201], v[84:87]
	s_waitcnt lgkmcnt(4)
	v_mfma_f32_16x16x32_bf16 v[80:83], v[174:177], v[210:213], v[80:83]
	v_mfma_f32_16x16x32_bf16 v[76:79], v[178:181], v[210:213], v[76:79]
	v_mfma_f32_16x16x32_bf16 v[72:75], v[182:185], v[210:213], v[72:75]
	v_mfma_f32_16x16x32_bf16 v[68:71], v[186:189], v[210:213], v[68:71]
	s_waitcnt lgkmcnt(3)
	v_mfma_f32_16x16x32_bf16 v[64:67], v[174:177], v[220:223], v[64:67]
	v_mfma_f32_16x16x32_bf16 v[60:63], v[178:181], v[220:223], v[60:63]
	v_mfma_f32_16x16x32_bf16 v[56:59], v[182:185], v[220:223], v[56:59]
	v_mfma_f32_16x16x32_bf16 v[52:55], v[186:189], v[220:223], v[52:55]
	s_waitcnt lgkmcnt(2)
	v_mfma_f32_16x16x32_bf16 v[48:51], v[174:177], v[224:227], v[48:51]
	v_mfma_f32_16x16x32_bf16 v[44:47], v[178:181], v[224:227], v[44:47]
	v_mfma_f32_16x16x32_bf16 v[40:43], v[182:185], v[224:227], v[40:43]
	v_mfma_f32_16x16x32_bf16 v[36:39], v[186:189], v[224:227], v[36:39]
	s_waitcnt lgkmcnt(1)
	v_mfma_f32_16x16x32_bf16 v[32:35], v[174:177], v[230:233], v[32:35]
	v_mfma_f32_16x16x32_bf16 v[28:31], v[178:181], v[230:233], v[28:31]
	v_mfma_f32_16x16x32_bf16 v[24:27], v[182:185], v[230:233], v[24:27]
	v_mfma_f32_16x16x32_bf16 v[20:23], v[186:189], v[230:233], v[20:23]
	s_waitcnt lgkmcnt(0)
	v_mfma_f32_16x16x32_bf16 v[16:19], v[174:177], v[234:237], v[16:19]
	v_mfma_f32_16x16x32_bf16 v[12:15], v[178:181], v[234:237], v[12:15]
	v_mfma_f32_16x16x32_bf16 v[8:11], v[182:185], v[234:237], v[8:11]
	v_mfma_f32_16x16x32_bf16 v[4:7], v[186:189], v[234:237], v[4:7]
	s_setprio 0
	s_add_u32 s2, s2, 64
	s_addc_u32 s3, s3, 0
	s_add_u32 s21, s21, 0x6000
	s_cmp_eq_u32 s21, 0x12000
	s_cselect_b32 s21, 0, s21
	s_add_u32 s22, s22, 0x6000
	s_cmp_eq_u32 s22, 0x12000
	s_cselect_b32 s22, 0, s22
	s_cmpk_eq_i32 s2, 0x1040
	s_waitcnt vmcnt(6)
	s_barrier
	s_cbranch_scc0 .LBB0_1459
; DEVI u32 pack2(float a, float b) { return f2bf(a) | (f2bf(b) << 16); }
;     ...
;       const char* As = smem + buf * 24576;
;       const char* Bs = As + 16384;
;       bf16x8 bfr[4];
; #pragma unroll
;       for (int j = 0; j < 4; ++j) bfr[j] = *(const bf16x8*)(Bs + (wn * 64 + j * 16 + l15) * 64 + rsw);
;       bf16x8 afr[8];
; #pragma unroll
;       for (int i = 0; i < 8; ++i) afr[i] = *(const bf16x8*)(As + (wm * 128 + i * 16 + l15) * 64 + rsw);
;       __builtin_amdgcn_s_setprio(1);
; #pragma unroll
;       for (int i = 0; i < 8; ++i) {
; #pragma unroll
;         for (int j = 0; j < 4; ++j) acc[i][j] = __builtin_amdgcn_mfma_f32_16x16x32_bf16(bfr[j], afr[i], acc[i][j], 0, 0, 0);
;       }
;     ...
; #pragma unroll
;     for (int i = 0; i < 8; ++i) {
;       const int row = m0 + wm * 128 + i * 16 + l15;
; #pragma unroll
;       for (int j = 0; j < 4; ++j) {
;         const int n = n0 + wn * 64 + j * 16 + quad * 4;
;         f32x4 a = acc[i][j];
;         if (EPI == EPI_Z) {
;           u16* dst;
;           if (n0 < 1536) dst = (u16*)(p.ws + W_ZA) + (size_t)row * LZA + n;
;           else if (n0 < 4736) dst = (u16*)(p.ws + W_ZB) + (size_t)row * LZB + (n - 1536);
;           else dst = (u16*)(p.ws + W_ZC) + (size_t)row * LZC + (n - 4736);
;           *(uint2*)dst = make_uint2(pack2(a[0], a[1]), pack2(a[2], a[3]));
;         } else if (EPI == EPI_RES) {
;           if (split) {
;             float* op = p.out + (size_t)row * D + n;
;             unsafeAtomicAdd(op, a[0]); unsafeAtomicAdd(op + 1, a[1]); unsafeAtomicAdd(op + 2, a[2]); unsafeAtomicAdd(op + 3, a[3]);
;           } else {
;             const float* xin = res_from_input ? xrow_in(p, 0, row) : p.out + (size_t)row * D;
;             float4 xv = *(const float4*)(xin + n);
;             float4 o = make_float4(xv.x + a[0], xv.y + a[1], xv.z + a[2], xv.w + a[3]);
;             *(float4*)(p.out + (size_t)row * D + n) = o;
;           }
;         } else {
;           float r0 = fmaxf(a[0], 0.f), r1 = fmaxf(a[1], 0.f), r2 = fmaxf(a[2], 0.f), r3 = fmaxf(a[3], 0.f);
;           u16* dst = (u16*)(p.ws + W_H) + (size_t)row * DFF + n;
;           *(uint2*)dst = make_uint2(pack2(r0 * r0, r1 * r1), pack2(r2 * r2, r3 * r3));
	v_add_u32_e32 v190, s21, v147
	v_add_u32_e32 v194, s21, v149
	v_add_u32_e32 v190, v190, v146
	ds_read_b128 v[138:141], v194 offset:16384
	ds_read_b128 v[150:153], v194 offset:17408
	ds_read_b128 v[154:157], v194 offset:18432
	ds_read_b128 v[158:161], v194 offset:19456
	ds_read_b128 v[162:165], v190
	ds_read_b128 v[166:169], v190 offset:1024
	ds_read_b128 v[170:173], v190 offset:2048
	ds_read_b128 v[174:177], v190 offset:3072
	ds_read_b128 v[178:181], v190 offset:4096
	ds_read_b128 v[182:185], v190 offset:5120
	ds_read_b128 v[186:189], v190 offset:6144
	ds_read_b128 v[190:193], v190 offset:7168
	s_setprio 1
	s_waitcnt lgkmcnt(7)
	v_mfma_f32_16x16x32_bf16 v[128:131], v[138:141], v[162:165], v[128:131]
	v_mfma_f32_16x16x32_bf16 v[124:127], v[150:153], v[162:165], v[124:127]
	v_mfma_f32_16x16x32_bf16 v[120:123], v[154:157], v[162:165], v[120:123]
	v_mfma_f32_16x16x32_bf16 v[116:119], v[158:161], v[162:165], v[116:119]
	s_waitcnt lgkmcnt(6)
	v_mfma_f32_16x16x32_bf16 v[112:115], v[138:141], v[166:169], v[112:115]
	v_mfma_f32_16x16x32_bf16 v[108:111], v[150:153], v[166:169], v[108:111]
	v_mfma_f32_16x16x32_bf16 v[162:165], v[154:157], v[166:169], v[104:107]
	v_mfma_f32_16x16x32_bf16 v[100:103], v[158:161], v[166:169], v[100:103]
	s_waitcnt lgkmcnt(5)
	v_mfma_f32_16x16x32_bf16 v[96:99], v[138:141], v[170:173], v[96:99]
	v_mfma_f32_16x16x32_bf16 v[92:95], v[150:153], v[170:173], v[92:95]
	v_mfma_f32_16x16x32_bf16 v[88:91], v[154:157], v[170:173], v[88:91]
	v_mfma_f32_16x16x32_bf16 v[84:87], v[158:161], v[170:173], v[84:87]
	s_waitcnt lgkmcnt(4)
	v_mfma_f32_16x16x32_bf16 v[80:83], v[138:141], v[174:177], v[80:83]
	v_mfma_f32_16x16x32_bf16 v[76:79], v[150:153], v[174:177], v[76:79]
	v_mfma_f32_16x16x32_bf16 v[72:75], v[154:157], v[174:177], v[72:75]
	v_mfma_f32_16x16x32_bf16 v[68:71], v[158:161], v[174:177], v[68:71]
	s_waitcnt lgkmcnt(3)
	v_mfma_f32_16x16x32_bf16 v[64:67], v[138:141], v[178:181], v[64:67]
	v_mfma_f32_16x16x32_bf16 v[60:63], v[150:153], v[178:181], v[60:63]
	v_mfma_f32_16x16x32_bf16 v[56:59], v[154:157], v[178:181], v[56:59]
	v_mfma_f32_16x16x32_bf16 v[52:55], v[158:161], v[178:181], v[52:55]
	s_waitcnt lgkmcnt(2)
	v_mfma_f32_16x16x32_bf16 v[48:51], v[138:141], v[182:185], v[48:51]
	v_mfma_f32_16x16x32_bf16 v[44:47], v[150:153], v[182:185], v[44:47]
	v_mfma_f32_16x16x32_bf16 v[40:43], v[154:157], v[182:185], v[40:43]
	v_mfma_f32_16x16x32_bf16 v[36:39], v[158:161], v[182:185], v[36:39]
	s_waitcnt lgkmcnt(1)
	v_mfma_f32_16x16x32_bf16 v[32:35], v[138:141], v[186:189], v[32:35]
	v_mfma_f32_16x16x32_bf16 v[28:31], v[150:153], v[186:189], v[28:31]
	v_mfma_f32_16x16x32_bf16 v[24:27], v[154:157], v[186:189], v[24:27]
	v_mfma_f32_16x16x32_bf16 v[20:23], v[158:161], v[186:189], v[20:23]
	s_waitcnt lgkmcnt(0)
	v_mfma_f32_16x16x32_bf16 v[16:19], v[138:141], v[190:193], v[16:19]
	v_mfma_f32_16x16x32_bf16 v[12:15], v[150:153], v[190:193], v[12:15]
	v_mfma_f32_16x16x32_bf16 v[8:11], v[154:157], v[190:193], v[8:11]
	v_mfma_f32_16x16x32_bf16 v[4:7], v[158:161], v[190:193], v[4:7]
	s_setprio 0
	s_waitcnt vmcnt(0)
	v_add_u32_e32 v104, s5, v142
	v_ashrrev_i32_e32 v105, 31, v104
	v_lshlrev_b64 v[138:139], 14, v[104:105]
	v_max_f32_e32 v105, v128, v128
	v_max_f32_e32 v128, 0, v105
	v_max_f32_e32 v105, v129, v129
	v_or_b32_e32 v106, s6, v143
	v_readlane_b32 s2, v251, 60
	v_max_f32_e32 v140, 0, v105
	v_max_f32_e32 v105, v130, v130
	v_readlane_b32 s3, v251, 61
	v_max_f32_e32 v129, 0, v105
	v_max_f32_e32 v105, v131, v131
	v_ashrrev_i32_e32 v107, 31, v106
	v_lshl_add_u64 v[138:139], s[2:3], 0, v[138:139]
	v_max_f32_e32 v141, 0, v105
	v_lshlrev_b64 v[106:107], 1, v[106:107]
	v_pk_mul_f32 v[128:129], v[128:129], v[128:129]
	v_lshl_add_u64 v[130:131], v[138:139], 0, v[106:107]
	v_pk_mul_f32 v[138:139], v[140:141], v[140:141]
	v_and_b32_sdwa v105, v129, v202 dst_sel:DWORD dst_unused:UNUSED_PAD src0_sel:WORD_1 src1_sel:DWORD
	v_and_b32_sdwa v140, v128, v202 dst_sel:DWORD dst_unused:UNUSED_PAD src0_sel:WORD_1 src1_sel:DWORD
	v_add3_u32 v105, v129, v105, s33
	v_and_b32_sdwa v129, v139, v202 dst_sel:DWORD dst_unused:UNUSED_PAD src0_sel:WORD_1 src1_sel:DWORD
	v_add3_u32 v128, v128, v140, s33
	v_and_b32_sdwa v140, v138, v202 dst_sel:DWORD dst_unused:UNUSED_PAD src0_sel:WORD_1 src1_sel:DWORD
	v_add3_u32 v129, v139, v129, s33
	v_add3_u32 v138, v138, v140, s33
	v_and_b32_e32 v129, 0xffff0000, v129
	v_and_b32_e32 v138, 0xffff0000, v138
	v_or_b32_sdwa v129, v129, v105 dst_sel:DWORD dst_unused:UNUSED_PAD src0_sel:DWORD src1_sel:WORD_1
	v_max_f32_e32 v105, v124, v124
	v_or_b32_sdwa v128, v138, v128 dst_sel:DWORD dst_unused:UNUSED_PAD src0_sel:DWORD src1_sel:WORD_1
	v_max_f32_e32 v124, 0, v105
	v_max_f32_e32 v105, v125, v125
	s_barrier
; DEVI u32 pack2(float a, float b) { return f2bf(a) | (f2bf(b) << 16); }
;     ...
; #pragma unroll
;     for (int i = 0; i < 8; ++i) {
;       const int row = m0 + wm * 128 + i * 16 + l15;
; #pragma unroll
;       for (int j = 0; j < 4; ++j) {
;         const int n = n0 + wn * 64 + j * 16 + quad * 4;
;         f32x4 a = acc[i][j];
;         if (EPI == EPI_Z) {
;           u16* dst;
;           if (n0 < 1536) dst = (u16*)(p.ws + W_ZA) + (size_t)row * LZA + n;
;           else if (n0 < 4736) dst = (u16*)(p.ws + W_ZB) + (size_t)row * LZB + (n - 1536);
;           else dst = (u16*)(p.ws + W_ZC) + (size_t)row * LZC + (n - 4736);
;           *(uint2*)dst = make_uint2(pack2(a[0], a[1]), pack2(a[2], a[3]));
;         } else if (EPI == EPI_RES) {
;           if (split) {
;             float* op = p.out + (size_t)row * D + n;
;             unsafeAtomicAdd(op, a[0]); unsafeAtomicAdd(op + 1, a[1]); unsafeAtomicAdd(op + 2, a[2]); unsafeAtomicAdd(op + 3, a[3]);
;           } else {
;             const float* xin = res_from_input ? xrow_in(p, 0, row) : p.out + (size_t)row * D;
;             float4 xv = *(const float4*)(xin + n);
;             float4 o = make_float4(xv.x + a[0], xv.y + a[1], xv.z + a[2], xv.w + a[3]);
;             *(float4*)(p.out + (size_t)row * D + n) = o;
;           }
;         } else {
;           float r0 = fmaxf(a[0], 0.f), r1 = fmaxf(a[1], 0.f), r2 = fmaxf(a[2], 0.f), r3 = fmaxf(a[3], 0.f);
;           u16* dst = (u16*)(p.ws + W_H) + (size_t)row * DFF + n;
;           *(uint2*)dst = make_uint2(pack2(r0 * r0, r1 * r1), pack2(r2 * r2, r3 * r3));
;         }
	global_store_dwordx2 v[130:131], v[128:129], off
	v_max_f32_e32 v128, 0, v105
	v_max_f32_e32 v105, v126, v126
	v_max_f32_e32 v125, 0, v105
	v_max_f32_e32 v105, v127, v127
	v_max_f32_e32 v129, 0, v105
	v_pk_mul_f32 v[124:125], v[124:125], v[124:125]
	v_pk_mul_f32 v[126:127], v[128:129], v[128:129]
	v_and_b32_sdwa v105, v125, v202 dst_sel:DWORD dst_unused:UNUSED_PAD src0_sel:WORD_1 src1_sel:DWORD
	v_and_b32_sdwa v128, v124, v202 dst_sel:DWORD dst_unused:UNUSED_PAD src0_sel:WORD_1 src1_sel:DWORD
	v_add3_u32 v105, v125, v105, s33
	v_and_b32_sdwa v125, v127, v202 dst_sel:DWORD dst_unused:UNUSED_PAD src0_sel:WORD_1 src1_sel:DWORD
	v_add3_u32 v124, v124, v128, s33
	v_and_b32_sdwa v128, v126, v202 dst_sel:DWORD dst_unused:UNUSED_PAD src0_sel:WORD_1 src1_sel:DWORD
	v_add3_u32 v125, v127, v125, s33
	v_add3_u32 v126, v126, v128, s33
	v_and_b32_e32 v125, 0xffff0000, v125
	v_and_b32_e32 v126, 0xffff0000, v126
	v_or_b32_sdwa v125, v125, v105 dst_sel:DWORD dst_unused:UNUSED_PAD src0_sel:DWORD src1_sel:WORD_1
	v_max_f32_e32 v105, v120, v120
	v_or_b32_sdwa v124, v126, v124 dst_sel:DWORD dst_unused:UNUSED_PAD src0_sel:DWORD src1_sel:WORD_1
	v_max_f32_e32 v120, 0, v105
	v_max_f32_e32 v105, v121, v121
	global_store_dwordx2 v[130:131], v[124:125], off offset:32
	v_max_f32_e32 v124, 0, v105
	v_max_f32_e32 v105, v122, v122
	v_max_f32_e32 v121, 0, v105
	v_max_f32_e32 v105, v123, v123
	v_max_f32_e32 v125, 0, v105
	v_pk_mul_f32 v[120:121], v[120:121], v[120:121]
	v_pk_mul_f32 v[122:123], v[124:125], v[124:125]
	v_and_b32_sdwa v105, v121, v202 dst_sel:DWORD dst_unused:UNUSED_PAD src0_sel:WORD_1 src1_sel:DWORD
	v_and_b32_sdwa v124, v120, v202 dst_sel:DWORD dst_unused:UNUSED_PAD src0_sel:WORD_1 src1_sel:DWORD
	v_add3_u32 v105, v121, v105, s33
	v_and_b32_sdwa v121, v123, v202 dst_sel:DWORD dst_unused:UNUSED_PAD src0_sel:WORD_1 src1_sel:DWORD
	v_add3_u32 v120, v120, v124, s33
	v_and_b32_sdwa v124, v122, v202 dst_sel:DWORD dst_unused:UNUSED_PAD src0_sel:WORD_1 src1_sel:DWORD
	v_add3_u32 v121, v123, v121, s33
	v_add3_u32 v122, v122, v124, s33
	v_and_b32_e32 v121, 0xffff0000, v121
	v_and_b32_e32 v122, 0xffff0000, v122
	v_or_b32_sdwa v121, v121, v105 dst_sel:DWORD dst_unused:UNUSED_PAD src0_sel:DWORD src1_sel:WORD_1
	v_max_f32_e32 v105, v116, v116
	v_or_b32_sdwa v120, v122, v120 dst_sel:DWORD dst_unused:UNUSED_PAD src0_sel:DWORD src1_sel:WORD_1
	v_max_f32_e32 v116, 0, v105
	v_max_f32_e32 v105, v117, v117
	global_store_dwordx2 v[130:131], v[120:121], off offset:64
	v_max_f32_e32 v120, 0, v105
	v_max_f32_e32 v105, v118, v118
	v_max_f32_e32 v117, 0, v105
	v_max_f32_e32 v105, v119, v119
	v_max_f32_e32 v121, 0, v105
	v_pk_mul_f32 v[116:117], v[116:117], v[116:117]
	v_pk_mul_f32 v[118:119], v[120:121], v[120:121]
	v_and_b32_sdwa v105, v117, v202 dst_sel:DWORD dst_unused:UNUSED_PAD src0_sel:WORD_1 src1_sel:DWORD
	v_and_b32_sdwa v120, v116, v202 dst_sel:DWORD dst_unused:UNUSED_PAD src0_sel:WORD_1 src1_sel:DWORD
	v_add3_u32 v116, v116, v120, s33
	v_add3_u32 v105, v117, v105, s33
	v_and_b32_sdwa v117, v119, v202 dst_sel:DWORD dst_unused:UNUSED_PAD src0_sel:WORD_1 src1_sel:DWORD
	v_and_b32_sdwa v120, v118, v202 dst_sel:DWORD dst_unused:UNUSED_PAD src0_sel:WORD_1 src1_sel:DWORD
	v_add3_u32 v117, v119, v117, s33
	v_add3_u32 v118, v118, v120, s33
	v_and_b32_e32 v117, 0xffff0000, v117
	v_and_b32_e32 v118, 0xffff0000, v118
	v_or_b32_sdwa v117, v117, v105 dst_sel:DWORD dst_unused:UNUSED_PAD src0_sel:DWORD src1_sel:WORD_1
	v_or_b32_sdwa v116, v118, v116 dst_sel:DWORD dst_unused:UNUSED_PAD src0_sel:DWORD src1_sel:WORD_1
	v_max_f32_e32 v105, v112, v112
	global_store_dwordx2 v[130:131], v[116:117], off offset:96
	v_or_b32_e32 v116, 16, v104
	v_max_f32_e32 v112, 0, v105
	v_max_f32_e32 v105, v113, v113
	v_ashrrev_i32_e32 v117, 31, v116
	v_max_f32_e32 v118, 0, v105
	v_max_f32_e32 v105, v114, v114
	v_lshlrev_b64 v[116:117], 14, v[116:117]
	v_max_f32_e32 v113, 0, v105
	v_max_f32_e32 v105, v115, v115
	v_lshl_add_u64 v[116:117], s[2:3], 0, v[116:117]
	v_max_f32_e32 v119, 0, v105
	v_pk_mul_f32 v[112:113], v[112:113], v[112:113]
	v_lshl_add_u64 v[114:115], v[116:117], 0, v[106:107]
	v_pk_mul_f32 v[116:117], v[118:119], v[118:119]
	v_and_b32_sdwa v105, v113, v202 dst_sel:DWORD dst_unused:UNUSED_PAD src0_sel:WORD_1 src1_sel:DWORD
	v_and_b32_sdwa v118, v112, v202 dst_sel:DWORD dst_unused:UNUSED_PAD src0_sel:WORD_1 src1_sel:DWORD
	v_add3_u32 v105, v113, v105, s33
	v_and_b32_sdwa v113, v117, v202 dst_sel:DWORD dst_unused:UNUSED_PAD src0_sel:WORD_1 src1_sel:DWORD
	v_add3_u32 v112, v112, v118, s33
	v_and_b32_sdwa v118, v116, v202 dst_sel:DWORD dst_unused:UNUSED_PAD src0_sel:WORD_1 src1_sel:DWORD
	v_add3_u32 v113, v117, v113, s33
	v_add3_u32 v116, v116, v118, s33
	v_and_b32_e32 v113, 0xffff0000, v113
	v_and_b32_e32 v116, 0xffff0000, v116
	v_or_b32_sdwa v113, v113, v105 dst_sel:DWORD dst_unused:UNUSED_PAD src0_sel:DWORD src1_sel:WORD_1
	v_max_f32_e32 v105, v108, v108
	v_or_b32_sdwa v112, v116, v112 dst_sel:DWORD dst_unused:UNUSED_PAD src0_sel:DWORD src1_sel:WORD_1
	v_max_f32_e32 v108, 0, v105
	v_max_f32_e32 v105, v109, v109
	global_store_dwordx2 v[114:115], v[112:113], off
	v_max_f32_e32 v112, 0, v105
	v_max_f32_e32 v105, v110, v110
	v_max_f32_e32 v109, 0, v105
	v_max_f32_e32 v105, v111, v111
	v_max_f32_e32 v113, 0, v105
	v_pk_mul_f32 v[108:109], v[108:109], v[108:109]
	v_pk_mul_f32 v[110:111], v[112:113], v[112:113]
	v_and_b32_sdwa v105, v109, v202 dst_sel:DWORD dst_unused:UNUSED_PAD src0_sel:WORD_1 src1_sel:DWORD
	v_and_b32_sdwa v112, v108, v202 dst_sel:DWORD dst_unused:UNUSED_PAD src0_sel:WORD_1 src1_sel:DWORD
	v_add3_u32 v108, v108, v112, s33
	v_add3_u32 v105, v109, v105, s33
; DEVI u32 pack2(float a, float b) { return f2bf(a) | (f2bf(b) << 16); }
;     ...
; #pragma unroll
;     for (int i = 0; i < 8; ++i) {
;       const int row = m0 + wm * 128 + i * 16 + l15;
; #pragma unroll
;       for (int j = 0; j < 4; ++j) {
;         const int n = n0 + wn * 64 + j * 16 + quad * 4;
;         f32x4 a = acc[i][j];
;         if (EPI == EPI_Z) {
;           u16* dst;
;           if (n0 < 1536) dst = (u16*)(p.ws + W_ZA) + (size_t)row * LZA + n;
;           else if (n0 < 4736) dst = (u16*)(p.ws + W_ZB) + (size_t)row * LZB + (n - 1536);
;           else dst = (u16*)(p.ws + W_ZC) + (size_t)row * LZC + (n - 4736);
;           *(uint2*)dst = make_uint2(pack2(a[0], a[1]), pack2(a[2], a[3]));
;         } else if (EPI == EPI_RES) {
;           if (split) {
;             float* op = p.out + (size_t)row * D + n;
;             unsafeAtomicAdd(op, a[0]); unsafeAtomicAdd(op + 1, a[1]); unsafeAtomicAdd(op + 2, a[2]); unsafeAtomicAdd(op + 3, a[3]);
;           } else {
;             const float* xin = res_from_input ? xrow_in(p, 0, row) : p.out + (size_t)row * D;
;             float4 xv = *(const float4*)(xin + n);
;             float4 o = make_float4(xv.x + a[0], xv.y + a[1], xv.z + a[2], xv.w + a[3]);
;             *(float4*)(p.out + (size_t)row * D + n) = o;
;           }
;         } else {
;           float r0 = fmaxf(a[0], 0.f), r1 = fmaxf(a[1], 0.f), r2 = fmaxf(a[2], 0.f), r3 = fmaxf(a[3], 0.f);
;           u16* dst = (u16*)(p.ws + W_H) + (size_t)row * DFF + n;
;           *(uint2*)dst = make_uint2(pack2(r0 * r0, r1 * r1), pack2(r2 * r2, r3 * r3));
;         }
	v_and_b32_sdwa v109, v111, v202 dst_sel:DWORD dst_unused:UNUSED_PAD src0_sel:WORD_1 src1_sel:DWORD
	v_and_b32_sdwa v112, v110, v202 dst_sel:DWORD dst_unused:UNUSED_PAD src0_sel:WORD_1 src1_sel:DWORD
	v_add3_u32 v109, v111, v109, s33
	v_add3_u32 v110, v110, v112, s33
	v_and_b32_e32 v109, 0xffff0000, v109
	v_and_b32_e32 v110, 0xffff0000, v110
	v_or_b32_sdwa v109, v109, v105 dst_sel:DWORD dst_unused:UNUSED_PAD src0_sel:DWORD src1_sel:WORD_1
	v_or_b32_sdwa v108, v110, v108 dst_sel:DWORD dst_unused:UNUSED_PAD src0_sel:DWORD src1_sel:WORD_1
	v_max_f32_e32 v105, v162, v162
	global_store_dwordx2 v[114:115], v[108:109], off offset:32
	v_max_f32_e32 v108, 0, v105
	v_max_f32_e32 v105, v163, v163
	v_max_f32_e32 v110, 0, v105
	v_max_f32_e32 v105, v164, v164
	v_max_f32_e32 v109, 0, v105
	v_max_f32_e32 v105, v165, v165
	v_max_f32_e32 v111, 0, v105
	v_pk_mul_f32 v[108:109], v[108:109], v[108:109]
	v_pk_mul_f32 v[110:111], v[110:111], v[110:111]
	v_and_b32_sdwa v105, v109, v202 dst_sel:DWORD dst_unused:UNUSED_PAD src0_sel:WORD_1 src1_sel:DWORD
	v_and_b32_sdwa v112, v108, v202 dst_sel:DWORD dst_unused:UNUSED_PAD src0_sel:WORD_1 src1_sel:DWORD
	v_add3_u32 v108, v108, v112, s33
	v_add3_u32 v105, v109, v105, s33
	v_and_b32_sdwa v109, v111, v202 dst_sel:DWORD dst_unused:UNUSED_PAD src0_sel:WORD_1 src1_sel:DWORD
	v_and_b32_sdwa v112, v110, v202 dst_sel:DWORD dst_unused:UNUSED_PAD src0_sel:WORD_1 src1_sel:DWORD
	v_add3_u32 v109, v111, v109, s33
	v_add3_u32 v110, v110, v112, s33
	v_and_b32_e32 v109, 0xffff0000, v109
	v_and_b32_e32 v110, 0xffff0000, v110
	v_or_b32_sdwa v109, v109, v105 dst_sel:DWORD dst_unused:UNUSED_PAD src0_sel:DWORD src1_sel:WORD_1
	v_or_b32_sdwa v108, v110, v108 dst_sel:DWORD dst_unused:UNUSED_PAD src0_sel:DWORD src1_sel:WORD_1
	v_max_f32_e32 v101, v101, v101
	global_store_dwordx2 v[114:115], v[108:109], off offset:64
	v_max_f32_e32 v100, v100, v100
	v_max_f32_e32 v108, 0, v101
	v_max_f32_e32 v101, v102, v102
	v_max_f32_e32 v100, 0, v100
	v_max_f32_e32 v101, 0, v101
	v_max_f32_e32 v102, v103, v103
	v_max_f32_e32 v109, 0, v102
	v_pk_mul_f32 v[100:101], v[100:101], v[100:101]
	v_pk_mul_f32 v[102:103], v[108:109], v[108:109]
	v_and_b32_sdwa v105, v101, v202 dst_sel:DWORD dst_unused:UNUSED_PAD src0_sel:WORD_1 src1_sel:DWORD
	v_and_b32_sdwa v108, v100, v202 dst_sel:DWORD dst_unused:UNUSED_PAD src0_sel:WORD_1 src1_sel:DWORD
	v_add3_u32 v100, v100, v108, s33
	v_add3_u32 v101, v101, v105, s33
	v_and_b32_sdwa v105, v103, v202 dst_sel:DWORD dst_unused:UNUSED_PAD src0_sel:WORD_1 src1_sel:DWORD
	v_and_b32_sdwa v108, v102, v202 dst_sel:DWORD dst_unused:UNUSED_PAD src0_sel:WORD_1 src1_sel:DWORD
	v_add3_u32 v103, v103, v105, s33
	v_add3_u32 v102, v102, v108, s33
	v_and_b32_e32 v103, 0xffff0000, v103
	v_and_b32_e32 v102, 0xffff0000, v102
	v_or_b32_sdwa v101, v103, v101 dst_sel:DWORD dst_unused:UNUSED_PAD src0_sel:DWORD src1_sel:WORD_1
	v_or_b32_sdwa v100, v102, v100 dst_sel:DWORD dst_unused:UNUSED_PAD src0_sel:DWORD src1_sel:WORD_1
	global_store_dwordx2 v[114:115], v[100:101], off offset:96
	v_or_b32_e32 v100, 32, v104
	v_max_f32_e32 v97, v97, v97
	v_ashrrev_i32_e32 v101, 31, v100
	v_max_f32_e32 v96, v96, v96
	v_max_f32_e32 v102, 0, v97
	v_max_f32_e32 v97, v98, v98
	v_lshlrev_b64 v[100:101], 14, v[100:101]
	v_max_f32_e32 v96, 0, v96
	v_max_f32_e32 v97, 0, v97
	v_max_f32_e32 v98, v99, v99
	v_lshl_add_u64 v[100:101], s[2:3], 0, v[100:101]
	v_max_f32_e32 v103, 0, v98
	v_pk_mul_f32 v[96:97], v[96:97], v[96:97]
	v_lshl_add_u64 v[98:99], v[100:101], 0, v[106:107]
	v_pk_mul_f32 v[100:101], v[102:103], v[102:103]
	v_and_b32_sdwa v102, v97, v202 dst_sel:DWORD dst_unused:UNUSED_PAD src0_sel:WORD_1 src1_sel:DWORD
	v_and_b32_sdwa v103, v96, v202 dst_sel:DWORD dst_unused:UNUSED_PAD src0_sel:WORD_1 src1_sel:DWORD
	v_add3_u32 v96, v96, v103, s33
	v_add3_u32 v97, v97, v102, s33
	v_and_b32_sdwa v102, v101, v202 dst_sel:DWORD dst_unused:UNUSED_PAD src0_sel:WORD_1 src1_sel:DWORD
	v_and_b32_sdwa v103, v100, v202 dst_sel:DWORD dst_unused:UNUSED_PAD src0_sel:WORD_1 src1_sel:DWORD
	v_add3_u32 v101, v101, v102, s33
	v_add3_u32 v100, v100, v103, s33
	v_and_b32_e32 v101, 0xffff0000, v101
	v_and_b32_e32 v100, 0xffff0000, v100
	v_or_b32_sdwa v97, v101, v97 dst_sel:DWORD dst_unused:UNUSED_PAD src0_sel:DWORD src1_sel:WORD_1
	v_or_b32_sdwa v96, v100, v96 dst_sel:DWORD dst_unused:UNUSED_PAD src0_sel:DWORD src1_sel:WORD_1
	v_max_f32_e32 v93, v93, v93
	global_store_dwordx2 v[98:99], v[96:97], off
	v_max_f32_e32 v92, v92, v92
	v_max_f32_e32 v96, 0, v93
	v_max_f32_e32 v93, v94, v94
	v_max_f32_e32 v92, 0, v92
	v_max_f32_e32 v93, 0, v93
	v_max_f32_e32 v94, v95, v95
	v_max_f32_e32 v97, 0, v94
	v_pk_mul_f32 v[92:93], v[92:93], v[92:93]
	v_pk_mul_f32 v[94:95], v[96:97], v[96:97]
	v_and_b32_sdwa v96, v93, v202 dst_sel:DWORD dst_unused:UNUSED_PAD src0_sel:WORD_1 src1_sel:DWORD
	v_and_b32_sdwa v97, v92, v202 dst_sel:DWORD dst_unused:UNUSED_PAD src0_sel:WORD_1 src1_sel:DWORD
	v_add3_u32 v92, v92, v97, s33
	v_add3_u32 v93, v93, v96, s33
	v_and_b32_sdwa v96, v95, v202 dst_sel:DWORD dst_unused:UNUSED_PAD src0_sel:WORD_1 src1_sel:DWORD
	v_and_b32_sdwa v97, v94, v202 dst_sel:DWORD dst_unused:UNUSED_PAD src0_sel:WORD_1 src1_sel:DWORD
	v_add3_u32 v95, v95, v96, s33
	v_add3_u32 v94, v94, v97, s33
	v_and_b32_e32 v95, 0xffff0000, v95
	v_and_b32_e32 v94, 0xffff0000, v94
	v_or_b32_sdwa v93, v95, v93 dst_sel:DWORD dst_unused:UNUSED_PAD src0_sel:DWORD src1_sel:WORD_1
	v_or_b32_sdwa v92, v94, v92 dst_sel:DWORD dst_unused:UNUSED_PAD src0_sel:DWORD src1_sel:WORD_1
	v_max_f32_e32 v89, v89, v89
	global_store_dwordx2 v[98:99], v[92:93], off offset:32
	v_max_f32_e32 v88, v88, v88
	v_max_f32_e32 v92, 0, v89
; DEVI u32 pack2(float a, float b) { return f2bf(a) | (f2bf(b) << 16); }
;     ...
; #pragma unroll
;     for (int i = 0; i < 8; ++i) {
;       const int row = m0 + wm * 128 + i * 16 + l15;
; #pragma unroll
;       for (int j = 0; j < 4; ++j) {
;         const int n = n0 + wn * 64 + j * 16 + quad * 4;
;         f32x4 a = acc[i][j];
;         if (EPI == EPI_Z) {
;           u16* dst;
;           if (n0 < 1536) dst = (u16*)(p.ws + W_ZA) + (size_t)row * LZA + n;
;           else if (n0 < 4736) dst = (u16*)(p.ws + W_ZB) + (size_t)row * LZB + (n - 1536);
;           else dst = (u16*)(p.ws + W_ZC) + (size_t)row * LZC + (n - 4736);
;           *(uint2*)dst = make_uint2(pack2(a[0], a[1]), pack2(a[2], a[3]));
;         } else if (EPI == EPI_RES) {
;           if (split) {
;             float* op = p.out + (size_t)row * D + n;
;             unsafeAtomicAdd(op, a[0]); unsafeAtomicAdd(op + 1, a[1]); unsafeAtomicAdd(op + 2, a[2]); unsafeAtomicAdd(op + 3, a[3]);
;           } else {
;             const float* xin = res_from_input ? xrow_in(p, 0, row) : p.out + (size_t)row * D;
;             float4 xv = *(const float4*)(xin + n);
;             float4 o = make_float4(xv.x + a[0], xv.y + a[1], xv.z + a[2], xv.w + a[3]);
;             *(float4*)(p.out + (size_t)row * D + n) = o;
;           }
;         } else {
;           float r0 = fmaxf(a[0], 0.f), r1 = fmaxf(a[1], 0.f), r2 = fmaxf(a[2], 0.f), r3 = fmaxf(a[3], 0.f);
;           u16* dst = (u16*)(p.ws + W_H) + (size_t)row * DFF + n;
;           *(uint2*)dst = make_uint2(pack2(r0 * r0, r1 * r1), pack2(r2 * r2, r3 * r3));
;         }
	v_max_f32_e32 v89, v90, v90
	v_max_f32_e32 v88, 0, v88
	v_max_f32_e32 v89, 0, v89
	v_max_f32_e32 v90, v91, v91
	v_max_f32_e32 v93, 0, v90
	v_pk_mul_f32 v[88:89], v[88:89], v[88:89]
	v_pk_mul_f32 v[90:91], v[92:93], v[92:93]
	v_and_b32_sdwa v92, v89, v202 dst_sel:DWORD dst_unused:UNUSED_PAD src0_sel:WORD_1 src1_sel:DWORD
	v_and_b32_sdwa v93, v88, v202 dst_sel:DWORD dst_unused:UNUSED_PAD src0_sel:WORD_1 src1_sel:DWORD
	v_add3_u32 v88, v88, v93, s33
	v_add3_u32 v89, v89, v92, s33
	v_and_b32_sdwa v92, v91, v202 dst_sel:DWORD dst_unused:UNUSED_PAD src0_sel:WORD_1 src1_sel:DWORD
	v_and_b32_sdwa v93, v90, v202 dst_sel:DWORD dst_unused:UNUSED_PAD src0_sel:WORD_1 src1_sel:DWORD
	v_add3_u32 v91, v91, v92, s33
	v_add3_u32 v90, v90, v93, s33
	v_and_b32_e32 v91, 0xffff0000, v91
	v_and_b32_e32 v90, 0xffff0000, v90
	v_or_b32_sdwa v89, v91, v89 dst_sel:DWORD dst_unused:UNUSED_PAD src0_sel:DWORD src1_sel:WORD_1
	v_or_b32_sdwa v88, v90, v88 dst_sel:DWORD dst_unused:UNUSED_PAD src0_sel:DWORD src1_sel:WORD_1
	v_max_f32_e32 v85, v85, v85
	global_store_dwordx2 v[98:99], v[88:89], off offset:64
	v_max_f32_e32 v84, v84, v84
	v_max_f32_e32 v88, 0, v85
	v_max_f32_e32 v85, v86, v86
	v_max_f32_e32 v84, 0, v84
	v_max_f32_e32 v85, 0, v85
	v_max_f32_e32 v86, v87, v87
	v_max_f32_e32 v89, 0, v86
	v_pk_mul_f32 v[84:85], v[84:85], v[84:85]
	v_pk_mul_f32 v[86:87], v[88:89], v[88:89]
	v_and_b32_sdwa v88, v85, v202 dst_sel:DWORD dst_unused:UNUSED_PAD src0_sel:WORD_1 src1_sel:DWORD
	v_and_b32_sdwa v89, v84, v202 dst_sel:DWORD dst_unused:UNUSED_PAD src0_sel:WORD_1 src1_sel:DWORD
	v_add3_u32 v84, v84, v89, s33
	v_add3_u32 v85, v85, v88, s33
	v_and_b32_sdwa v88, v87, v202 dst_sel:DWORD dst_unused:UNUSED_PAD src0_sel:WORD_1 src1_sel:DWORD
	v_and_b32_sdwa v89, v86, v202 dst_sel:DWORD dst_unused:UNUSED_PAD src0_sel:WORD_1 src1_sel:DWORD
	v_add3_u32 v87, v87, v88, s33
	v_add3_u32 v86, v86, v89, s33
	v_and_b32_e32 v87, 0xffff0000, v87
	v_and_b32_e32 v86, 0xffff0000, v86
	v_or_b32_sdwa v85, v87, v85 dst_sel:DWORD dst_unused:UNUSED_PAD src0_sel:DWORD src1_sel:WORD_1
	v_or_b32_sdwa v84, v86, v84 dst_sel:DWORD dst_unused:UNUSED_PAD src0_sel:DWORD src1_sel:WORD_1
	global_store_dwordx2 v[98:99], v[84:85], off offset:96
	v_or_b32_e32 v84, 48, v104
	v_max_f32_e32 v81, v81, v81
	v_ashrrev_i32_e32 v85, 31, v84
	v_max_f32_e32 v80, v80, v80
	v_max_f32_e32 v86, 0, v81
	v_max_f32_e32 v81, v82, v82
	v_lshlrev_b64 v[84:85], 14, v[84:85]
	v_max_f32_e32 v80, 0, v80
	v_max_f32_e32 v81, 0, v81
	v_max_f32_e32 v82, v83, v83
	v_lshl_add_u64 v[84:85], s[2:3], 0, v[84:85]
	v_max_f32_e32 v87, 0, v82
	v_pk_mul_f32 v[80:81], v[80:81], v[80:81]
	v_lshl_add_u64 v[82:83], v[84:85], 0, v[106:107]
	v_pk_mul_f32 v[84:85], v[86:87], v[86:87]
	v_and_b32_sdwa v86, v81, v202 dst_sel:DWORD dst_unused:UNUSED_PAD src0_sel:WORD_1 src1_sel:DWORD
	v_and_b32_sdwa v87, v80, v202 dst_sel:DWORD dst_unused:UNUSED_PAD src0_sel:WORD_1 src1_sel:DWORD
	v_add3_u32 v80, v80, v87, s33
	v_add3_u32 v81, v81, v86, s33
	v_and_b32_sdwa v86, v85, v202 dst_sel:DWORD dst_unused:UNUSED_PAD src0_sel:WORD_1 src1_sel:DWORD
	v_and_b32_sdwa v87, v84, v202 dst_sel:DWORD dst_unused:UNUSED_PAD src0_sel:WORD_1 src1_sel:DWORD
	v_add3_u32 v85, v85, v86, s33
	v_add3_u32 v84, v84, v87, s33
	v_and_b32_e32 v85, 0xffff0000, v85
	v_and_b32_e32 v84, 0xffff0000, v84
	v_or_b32_sdwa v81, v85, v81 dst_sel:DWORD dst_unused:UNUSED_PAD src0_sel:DWORD src1_sel:WORD_1
	v_or_b32_sdwa v80, v84, v80 dst_sel:DWORD dst_unused:UNUSED_PAD src0_sel:DWORD src1_sel:WORD_1
	v_max_f32_e32 v77, v77, v77
	global_store_dwordx2 v[82:83], v[80:81], off
	v_max_f32_e32 v76, v76, v76
	v_max_f32_e32 v80, 0, v77
	v_max_f32_e32 v77, v78, v78
	v_max_f32_e32 v76, 0, v76
	v_max_f32_e32 v77, 0, v77
	v_max_f32_e32 v78, v79, v79
	v_max_f32_e32 v81, 0, v78
	v_pk_mul_f32 v[76:77], v[76:77], v[76:77]
	v_pk_mul_f32 v[78:79], v[80:81], v[80:81]
	v_and_b32_sdwa v80, v77, v202 dst_sel:DWORD dst_unused:UNUSED_PAD src0_sel:WORD_1 src1_sel:DWORD
	v_and_b32_sdwa v81, v76, v202 dst_sel:DWORD dst_unused:UNUSED_PAD src0_sel:WORD_1 src1_sel:DWORD
	v_add3_u32 v76, v76, v81, s33
	v_add3_u32 v77, v77, v80, s33
	v_and_b32_sdwa v80, v79, v202 dst_sel:DWORD dst_unused:UNUSED_PAD src0_sel:WORD_1 src1_sel:DWORD
	v_and_b32_sdwa v81, v78, v202 dst_sel:DWORD dst_unused:UNUSED_PAD src0_sel:WORD_1 src1_sel:DWORD
	v_add3_u32 v79, v79, v80, s33
	v_add3_u32 v78, v78, v81, s33
	v_and_b32_e32 v79, 0xffff0000, v79
	v_and_b32_e32 v78, 0xffff0000, v78
	v_or_b32_sdwa v77, v79, v77 dst_sel:DWORD dst_unused:UNUSED_PAD src0_sel:DWORD src1_sel:WORD_1
	v_or_b32_sdwa v76, v78, v76 dst_sel:DWORD dst_unused:UNUSED_PAD src0_sel:DWORD src1_sel:WORD_1
	v_max_f32_e32 v73, v73, v73
	global_store_dwordx2 v[82:83], v[76:77], off offset:32
	v_max_f32_e32 v72, v72, v72
	v_max_f32_e32 v76, 0, v73
	v_max_f32_e32 v73, v74, v74
	v_max_f32_e32 v72, 0, v72
	v_max_f32_e32 v73, 0, v73
	v_max_f32_e32 v74, v75, v75
	v_max_f32_e32 v77, 0, v74
	v_pk_mul_f32 v[72:73], v[72:73], v[72:73]
	v_pk_mul_f32 v[74:75], v[76:77], v[76:77]
	v_and_b32_sdwa v76, v73, v202 dst_sel:DWORD dst_unused:UNUSED_PAD src0_sel:WORD_1 src1_sel:DWORD
	v_and_b32_sdwa v77, v72, v202 dst_sel:DWORD dst_unused:UNUSED_PAD src0_sel:WORD_1 src1_sel:DWORD
	v_add3_u32 v72, v72, v77, s33
	v_add3_u32 v73, v73, v76, s33
	v_and_b32_sdwa v76, v75, v202 dst_sel:DWORD dst_unused:UNUSED_PAD src0_sel:WORD_1 src1_sel:DWORD
	v_and_b32_sdwa v77, v74, v202 dst_sel:DWORD dst_unused:UNUSED_PAD src0_sel:WORD_1 src1_sel:DWORD
	v_add3_u32 v75, v75, v76, s33
	v_add3_u32 v74, v74, v77, s33
	v_and_b32_e32 v75, 0xffff0000, v75
	v_and_b32_e32 v74, 0xffff0000, v74
	v_or_b32_sdwa v73, v75, v73 dst_sel:DWORD dst_unused:UNUSED_PAD src0_sel:DWORD src1_sel:WORD_1
; DEVI u32 pack2(float a, float b) { return f2bf(a) | (f2bf(b) << 16); }
;     ...
; #pragma unroll
;     for (int i = 0; i < 8; ++i) {
;       const int row = m0 + wm * 128 + i * 16 + l15;
; #pragma unroll
;       for (int j = 0; j < 4; ++j) {
;         const int n = n0 + wn * 64 + j * 16 + quad * 4;
;         f32x4 a = acc[i][j];
;         if (EPI == EPI_Z) {
;           u16* dst;
;           if (n0 < 1536) dst = (u16*)(p.ws + W_ZA) + (size_t)row * LZA + n;
;           else if (n0 < 4736) dst = (u16*)(p.ws + W_ZB) + (size_t)row * LZB + (n - 1536);
;           else dst = (u16*)(p.ws + W_ZC) + (size_t)row * LZC + (n - 4736);
;           *(uint2*)dst = make_uint2(pack2(a[0], a[1]), pack2(a[2], a[3]));
;         } else if (EPI == EPI_RES) {
;           if (split) {
;             float* op = p.out + (size_t)row * D + n;
;             unsafeAtomicAdd(op, a[0]); unsafeAtomicAdd(op + 1, a[1]); unsafeAtomicAdd(op + 2, a[2]); unsafeAtomicAdd(op + 3, a[3]);
;           } else {
;             const float* xin = res_from_input ? xrow_in(p, 0, row) : p.out + (size_t)row * D;
;             float4 xv = *(const float4*)(xin + n);
;             float4 o = make_float4(xv.x + a[0], xv.y + a[1], xv.z + a[2], xv.w + a[3]);
;             *(float4*)(p.out + (size_t)row * D + n) = o;
;           }
;         } else {
;           float r0 = fmaxf(a[0], 0.f), r1 = fmaxf(a[1], 0.f), r2 = fmaxf(a[2], 0.f), r3 = fmaxf(a[3], 0.f);
;           u16* dst = (u16*)(p.ws + W_H) + (size_t)row * DFF + n;
;           *(uint2*)dst = make_uint2(pack2(r0 * r0, r1 * r1), pack2(r2 * r2, r3 * r3));
;         }
	v_or_b32_sdwa v72, v74, v72 dst_sel:DWORD dst_unused:UNUSED_PAD src0_sel:DWORD src1_sel:WORD_1
	v_max_f32_e32 v69, v69, v69
	global_store_dwordx2 v[82:83], v[72:73], off offset:64
	v_max_f32_e32 v68, v68, v68
	v_max_f32_e32 v72, 0, v69
	v_max_f32_e32 v69, v70, v70
	v_max_f32_e32 v68, 0, v68
	v_max_f32_e32 v69, 0, v69
	v_max_f32_e32 v70, v71, v71
	v_max_f32_e32 v73, 0, v70
	v_pk_mul_f32 v[68:69], v[68:69], v[68:69]
	v_pk_mul_f32 v[70:71], v[72:73], v[72:73]
	v_and_b32_sdwa v72, v69, v202 dst_sel:DWORD dst_unused:UNUSED_PAD src0_sel:WORD_1 src1_sel:DWORD
	v_and_b32_sdwa v73, v68, v202 dst_sel:DWORD dst_unused:UNUSED_PAD src0_sel:WORD_1 src1_sel:DWORD
	v_add3_u32 v68, v68, v73, s33
	v_add3_u32 v69, v69, v72, s33
	v_and_b32_sdwa v72, v71, v202 dst_sel:DWORD dst_unused:UNUSED_PAD src0_sel:WORD_1 src1_sel:DWORD
	v_and_b32_sdwa v73, v70, v202 dst_sel:DWORD dst_unused:UNUSED_PAD src0_sel:WORD_1 src1_sel:DWORD
	v_add3_u32 v71, v71, v72, s33
	v_add3_u32 v70, v70, v73, s33
	v_and_b32_e32 v71, 0xffff0000, v71
	v_and_b32_e32 v70, 0xffff0000, v70
	v_or_b32_sdwa v69, v71, v69 dst_sel:DWORD dst_unused:UNUSED_PAD src0_sel:DWORD src1_sel:WORD_1
	v_or_b32_sdwa v68, v70, v68 dst_sel:DWORD dst_unused:UNUSED_PAD src0_sel:DWORD src1_sel:WORD_1
	global_store_dwordx2 v[82:83], v[68:69], off offset:96
	v_or_b32_e32 v68, 64, v104
	v_max_f32_e32 v65, v65, v65
	v_ashrrev_i32_e32 v69, 31, v68
	v_max_f32_e32 v64, v64, v64
	v_max_f32_e32 v70, 0, v65
	v_max_f32_e32 v65, v66, v66
	v_lshlrev_b64 v[68:69], 14, v[68:69]
	v_max_f32_e32 v64, 0, v64
	v_max_f32_e32 v65, 0, v65
	v_max_f32_e32 v66, v67, v67
	v_lshl_add_u64 v[68:69], s[2:3], 0, v[68:69]
	v_max_f32_e32 v71, 0, v66
	v_pk_mul_f32 v[64:65], v[64:65], v[64:65]
	v_lshl_add_u64 v[66:67], v[68:69], 0, v[106:107]
	v_pk_mul_f32 v[68:69], v[70:71], v[70:71]
	v_and_b32_sdwa v70, v65, v202 dst_sel:DWORD dst_unused:UNUSED_PAD src0_sel:WORD_1 src1_sel:DWORD
	v_and_b32_sdwa v71, v64, v202 dst_sel:DWORD dst_unused:UNUSED_PAD src0_sel:WORD_1 src1_sel:DWORD
	v_add3_u32 v64, v64, v71, s33
	v_add3_u32 v65, v65, v70, s33
	v_and_b32_sdwa v70, v69, v202 dst_sel:DWORD dst_unused:UNUSED_PAD src0_sel:WORD_1 src1_sel:DWORD
	v_and_b32_sdwa v71, v68, v202 dst_sel:DWORD dst_unused:UNUSED_PAD src0_sel:WORD_1 src1_sel:DWORD
	v_add3_u32 v69, v69, v70, s33
	v_add3_u32 v68, v68, v71, s33
	v_and_b32_e32 v69, 0xffff0000, v69
	v_and_b32_e32 v68, 0xffff0000, v68
	v_or_b32_sdwa v65, v69, v65 dst_sel:DWORD dst_unused:UNUSED_PAD src0_sel:DWORD src1_sel:WORD_1
	v_or_b32_sdwa v64, v68, v64 dst_sel:DWORD dst_unused:UNUSED_PAD src0_sel:DWORD src1_sel:WORD_1
	v_max_f32_e32 v61, v61, v61
	global_store_dwordx2 v[66:67], v[64:65], off
	v_max_f32_e32 v60, v60, v60
	v_max_f32_e32 v64, 0, v61
	v_max_f32_e32 v61, v62, v62
	v_max_f32_e32 v60, 0, v60
	v_max_f32_e32 v61, 0, v61
	v_max_f32_e32 v62, v63, v63
	v_max_f32_e32 v65, 0, v62
	v_pk_mul_f32 v[60:61], v[60:61], v[60:61]
	v_pk_mul_f32 v[62:63], v[64:65], v[64:65]
	v_and_b32_sdwa v64, v61, v202 dst_sel:DWORD dst_unused:UNUSED_PAD src0_sel:WORD_1 src1_sel:DWORD
	v_and_b32_sdwa v65, v60, v202 dst_sel:DWORD dst_unused:UNUSED_PAD src0_sel:WORD_1 src1_sel:DWORD
	v_add3_u32 v60, v60, v65, s33
	v_add3_u32 v61, v61, v64, s33
	v_and_b32_sdwa v64, v63, v202 dst_sel:DWORD dst_unused:UNUSED_PAD src0_sel:WORD_1 src1_sel:DWORD
	v_and_b32_sdwa v65, v62, v202 dst_sel:DWORD dst_unused:UNUSED_PAD src0_sel:WORD_1 src1_sel:DWORD
	v_add3_u32 v63, v63, v64, s33
	v_add3_u32 v62, v62, v65, s33
	v_and_b32_e32 v63, 0xffff0000, v63
	v_and_b32_e32 v62, 0xffff0000, v62
	v_or_b32_sdwa v61, v63, v61 dst_sel:DWORD dst_unused:UNUSED_PAD src0_sel:DWORD src1_sel:WORD_1
	v_or_b32_sdwa v60, v62, v60 dst_sel:DWORD dst_unused:UNUSED_PAD src0_sel:DWORD src1_sel:WORD_1
	v_max_f32_e32 v57, v57, v57
	global_store_dwordx2 v[66:67], v[60:61], off offset:32
	v_max_f32_e32 v56, v56, v56
	v_max_f32_e32 v60, 0, v57
	v_max_f32_e32 v57, v58, v58
	v_max_f32_e32 v56, 0, v56
	v_max_f32_e32 v57, 0, v57
	v_max_f32_e32 v58, v59, v59
	v_max_f32_e32 v61, 0, v58
	v_pk_mul_f32 v[56:57], v[56:57], v[56:57]
	v_pk_mul_f32 v[58:59], v[60:61], v[60:61]
	v_and_b32_sdwa v60, v57, v202 dst_sel:DWORD dst_unused:UNUSED_PAD src0_sel:WORD_1 src1_sel:DWORD
	v_and_b32_sdwa v61, v56, v202 dst_sel:DWORD dst_unused:UNUSED_PAD src0_sel:WORD_1 src1_sel:DWORD
	v_add3_u32 v56, v56, v61, s33
	v_add3_u32 v57, v57, v60, s33
	v_and_b32_sdwa v60, v59, v202 dst_sel:DWORD dst_unused:UNUSED_PAD src0_sel:WORD_1 src1_sel:DWORD
	v_and_b32_sdwa v61, v58, v202 dst_sel:DWORD dst_unused:UNUSED_PAD src0_sel:WORD_1 src1_sel:DWORD
	v_add3_u32 v59, v59, v60, s33
	v_add3_u32 v58, v58, v61, s33
	v_and_b32_e32 v59, 0xffff0000, v59
	v_and_b32_e32 v58, 0xffff0000, v58
	v_or_b32_sdwa v57, v59, v57 dst_sel:DWORD dst_unused:UNUSED_PAD src0_sel:DWORD src1_sel:WORD_1
	v_or_b32_sdwa v56, v58, v56 dst_sel:DWORD dst_unused:UNUSED_PAD src0_sel:DWORD src1_sel:WORD_1
	v_max_f32_e32 v53, v53, v53
	global_store_dwordx2 v[66:67], v[56:57], off offset:64
	v_max_f32_e32 v52, v52, v52
	v_max_f32_e32 v56, 0, v53
	v_max_f32_e32 v53, v54, v54
	v_max_f32_e32 v52, 0, v52
	v_max_f32_e32 v53, 0, v53
	v_max_f32_e32 v54, v55, v55
	v_max_f32_e32 v57, 0, v54
	v_pk_mul_f32 v[52:53], v[52:53], v[52:53]
	v_pk_mul_f32 v[54:55], v[56:57], v[56:57]
	v_and_b32_sdwa v56, v53, v202 dst_sel:DWORD dst_unused:UNUSED_PAD src0_sel:WORD_1 src1_sel:DWORD
	v_and_b32_sdwa v57, v52, v202 dst_sel:DWORD dst_unused:UNUSED_PAD src0_sel:WORD_1 src1_sel:DWORD
	v_add3_u32 v52, v52, v57, s33
	v_add3_u32 v53, v53, v56, s33
	v_and_b32_sdwa v56, v55, v202 dst_sel:DWORD dst_unused:UNUSED_PAD src0_sel:WORD_1 src1_sel:DWORD
	v_and_b32_sdwa v57, v54, v202 dst_sel:DWORD dst_unused:UNUSED_PAD src0_sel:WORD_1 src1_sel:DWORD
; DEVI u32 pack2(float a, float b) { return f2bf(a) | (f2bf(b) << 16); }
;     ...
; #pragma unroll
;     for (int i = 0; i < 8; ++i) {
;       const int row = m0 + wm * 128 + i * 16 + l15;
; #pragma unroll
;       for (int j = 0; j < 4; ++j) {
;         const int n = n0 + wn * 64 + j * 16 + quad * 4;
;         f32x4 a = acc[i][j];
;         if (EPI == EPI_Z) {
;           u16* dst;
;           if (n0 < 1536) dst = (u16*)(p.ws + W_ZA) + (size_t)row * LZA + n;
;           else if (n0 < 4736) dst = (u16*)(p.ws + W_ZB) + (size_t)row * LZB + (n - 1536);
;           else dst = (u16*)(p.ws + W_ZC) + (size_t)row * LZC + (n - 4736);
;           *(uint2*)dst = make_uint2(pack2(a[0], a[1]), pack2(a[2], a[3]));
;         } else if (EPI == EPI_RES) {
;           if (split) {
;             float* op = p.out + (size_t)row * D + n;
;             unsafeAtomicAdd(op, a[0]); unsafeAtomicAdd(op + 1, a[1]); unsafeAtomicAdd(op + 2, a[2]); unsafeAtomicAdd(op + 3, a[3]);
;           } else {
;             const float* xin = res_from_input ? xrow_in(p, 0, row) : p.out + (size_t)row * D;
;             float4 xv = *(const float4*)(xin + n);
;             float4 o = make_float4(xv.x + a[0], xv.y + a[1], xv.z + a[2], xv.w + a[3]);
;             *(float4*)(p.out + (size_t)row * D + n) = o;
;           }
;         } else {
;           float r0 = fmaxf(a[0], 0.f), r1 = fmaxf(a[1], 0.f), r2 = fmaxf(a[2], 0.f), r3 = fmaxf(a[3], 0.f);
;           u16* dst = (u16*)(p.ws + W_H) + (size_t)row * DFF + n;
;           *(uint2*)dst = make_uint2(pack2(r0 * r0, r1 * r1), pack2(r2 * r2, r3 * r3));
;         }
	v_add3_u32 v55, v55, v56, s33
	v_add3_u32 v54, v54, v57, s33
	v_and_b32_e32 v55, 0xffff0000, v55
	v_and_b32_e32 v54, 0xffff0000, v54
	v_or_b32_sdwa v53, v55, v53 dst_sel:DWORD dst_unused:UNUSED_PAD src0_sel:DWORD src1_sel:WORD_1
	v_or_b32_sdwa v52, v54, v52 dst_sel:DWORD dst_unused:UNUSED_PAD src0_sel:DWORD src1_sel:WORD_1
	global_store_dwordx2 v[66:67], v[52:53], off offset:96
	v_or_b32_e32 v52, 0x50, v104
	v_max_f32_e32 v49, v49, v49
	v_ashrrev_i32_e32 v53, 31, v52
	v_max_f32_e32 v48, v48, v48
	v_max_f32_e32 v54, 0, v49
	v_max_f32_e32 v49, v50, v50
	v_lshlrev_b64 v[52:53], 14, v[52:53]
	v_max_f32_e32 v48, 0, v48
	v_max_f32_e32 v49, 0, v49
	v_max_f32_e32 v50, v51, v51
	v_lshl_add_u64 v[52:53], s[2:3], 0, v[52:53]
	v_max_f32_e32 v55, 0, v50
	v_pk_mul_f32 v[48:49], v[48:49], v[48:49]
	v_lshl_add_u64 v[50:51], v[52:53], 0, v[106:107]
	v_pk_mul_f32 v[52:53], v[54:55], v[54:55]
	v_and_b32_sdwa v54, v49, v202 dst_sel:DWORD dst_unused:UNUSED_PAD src0_sel:WORD_1 src1_sel:DWORD
	v_and_b32_sdwa v55, v48, v202 dst_sel:DWORD dst_unused:UNUSED_PAD src0_sel:WORD_1 src1_sel:DWORD
	v_add3_u32 v48, v48, v55, s33
	v_add3_u32 v49, v49, v54, s33
	v_and_b32_sdwa v54, v53, v202 dst_sel:DWORD dst_unused:UNUSED_PAD src0_sel:WORD_1 src1_sel:DWORD
	v_and_b32_sdwa v55, v52, v202 dst_sel:DWORD dst_unused:UNUSED_PAD src0_sel:WORD_1 src1_sel:DWORD
	v_add3_u32 v53, v53, v54, s33
	v_add3_u32 v52, v52, v55, s33
	v_and_b32_e32 v53, 0xffff0000, v53
	v_and_b32_e32 v52, 0xffff0000, v52
	v_or_b32_sdwa v49, v53, v49 dst_sel:DWORD dst_unused:UNUSED_PAD src0_sel:DWORD src1_sel:WORD_1
	v_or_b32_sdwa v48, v52, v48 dst_sel:DWORD dst_unused:UNUSED_PAD src0_sel:DWORD src1_sel:WORD_1
	v_max_f32_e32 v45, v45, v45
	global_store_dwordx2 v[50:51], v[48:49], off
	v_max_f32_e32 v44, v44, v44
	v_max_f32_e32 v48, 0, v45
	v_max_f32_e32 v45, v46, v46
	v_max_f32_e32 v44, 0, v44
	v_max_f32_e32 v45, 0, v45
	v_max_f32_e32 v46, v47, v47
	v_max_f32_e32 v49, 0, v46
	v_pk_mul_f32 v[44:45], v[44:45], v[44:45]
	v_pk_mul_f32 v[46:47], v[48:49], v[48:49]
	v_and_b32_sdwa v48, v45, v202 dst_sel:DWORD dst_unused:UNUSED_PAD src0_sel:WORD_1 src1_sel:DWORD
	v_and_b32_sdwa v49, v44, v202 dst_sel:DWORD dst_unused:UNUSED_PAD src0_sel:WORD_1 src1_sel:DWORD
	v_add3_u32 v44, v44, v49, s33
	v_add3_u32 v45, v45, v48, s33
	v_and_b32_sdwa v48, v47, v202 dst_sel:DWORD dst_unused:UNUSED_PAD src0_sel:WORD_1 src1_sel:DWORD
	v_and_b32_sdwa v49, v46, v202 dst_sel:DWORD dst_unused:UNUSED_PAD src0_sel:WORD_1 src1_sel:DWORD
	v_add3_u32 v47, v47, v48, s33
	v_add3_u32 v46, v46, v49, s33
	v_and_b32_e32 v47, 0xffff0000, v47
	v_and_b32_e32 v46, 0xffff0000, v46
	v_or_b32_sdwa v45, v47, v45 dst_sel:DWORD dst_unused:UNUSED_PAD src0_sel:DWORD src1_sel:WORD_1
	v_or_b32_sdwa v44, v46, v44 dst_sel:DWORD dst_unused:UNUSED_PAD src0_sel:DWORD src1_sel:WORD_1
	v_max_f32_e32 v41, v41, v41
	global_store_dwordx2 v[50:51], v[44:45], off offset:32
	v_max_f32_e32 v40, v40, v40
	v_max_f32_e32 v44, 0, v41
	v_max_f32_e32 v41, v42, v42
	v_max_f32_e32 v40, 0, v40
	v_max_f32_e32 v41, 0, v41
	v_max_f32_e32 v42, v43, v43
	v_max_f32_e32 v45, 0, v42
	v_pk_mul_f32 v[40:41], v[40:41], v[40:41]
	v_pk_mul_f32 v[42:43], v[44:45], v[44:45]
	v_and_b32_sdwa v44, v41, v202 dst_sel:DWORD dst_unused:UNUSED_PAD src0_sel:WORD_1 src1_sel:DWORD
	v_and_b32_sdwa v45, v40, v202 dst_sel:DWORD dst_unused:UNUSED_PAD src0_sel:WORD_1 src1_sel:DWORD
	v_add3_u32 v40, v40, v45, s33
	v_add3_u32 v41, v41, v44, s33
	v_and_b32_sdwa v44, v43, v202 dst_sel:DWORD dst_unused:UNUSED_PAD src0_sel:WORD_1 src1_sel:DWORD
	v_and_b32_sdwa v45, v42, v202 dst_sel:DWORD dst_unused:UNUSED_PAD src0_sel:WORD_1 src1_sel:DWORD
	v_add3_u32 v43, v43, v44, s33
	v_add3_u32 v42, v42, v45, s33
	v_and_b32_e32 v43, 0xffff0000, v43
	v_and_b32_e32 v42, 0xffff0000, v42
	v_or_b32_sdwa v41, v43, v41 dst_sel:DWORD dst_unused:UNUSED_PAD src0_sel:DWORD src1_sel:WORD_1
	v_or_b32_sdwa v40, v42, v40 dst_sel:DWORD dst_unused:UNUSED_PAD src0_sel:DWORD src1_sel:WORD_1
	v_max_f32_e32 v37, v37, v37
	global_store_dwordx2 v[50:51], v[40:41], off offset:64
	v_max_f32_e32 v36, v36, v36
	v_max_f32_e32 v40, 0, v37
	v_max_f32_e32 v37, v38, v38
	v_max_f32_e32 v36, 0, v36
	v_max_f32_e32 v37, 0, v37
	v_max_f32_e32 v38, v39, v39
	v_max_f32_e32 v41, 0, v38
	v_pk_mul_f32 v[36:37], v[36:37], v[36:37]
	v_pk_mul_f32 v[38:39], v[40:41], v[40:41]
	v_and_b32_sdwa v40, v37, v202 dst_sel:DWORD dst_unused:UNUSED_PAD src0_sel:WORD_1 src1_sel:DWORD
	v_and_b32_sdwa v41, v36, v202 dst_sel:DWORD dst_unused:UNUSED_PAD src0_sel:WORD_1 src1_sel:DWORD
	v_add3_u32 v36, v36, v41, s33
	v_add3_u32 v37, v37, v40, s33
	v_and_b32_sdwa v40, v39, v202 dst_sel:DWORD dst_unused:UNUSED_PAD src0_sel:WORD_1 src1_sel:DWORD
	v_and_b32_sdwa v41, v38, v202 dst_sel:DWORD dst_unused:UNUSED_PAD src0_sel:WORD_1 src1_sel:DWORD
	v_add3_u32 v39, v39, v40, s33
	v_add3_u32 v38, v38, v41, s33
	v_and_b32_e32 v39, 0xffff0000, v39
	v_and_b32_e32 v38, 0xffff0000, v38
	v_or_b32_sdwa v37, v39, v37 dst_sel:DWORD dst_unused:UNUSED_PAD src0_sel:DWORD src1_sel:WORD_1
	v_or_b32_sdwa v36, v38, v36 dst_sel:DWORD dst_unused:UNUSED_PAD src0_sel:DWORD src1_sel:WORD_1
	global_store_dwordx2 v[50:51], v[36:37], off offset:96
	v_or_b32_e32 v36, 0x60, v104
	v_max_f32_e32 v33, v33, v33
	v_ashrrev_i32_e32 v37, 31, v36
	v_max_f32_e32 v32, v32, v32
	v_max_f32_e32 v38, 0, v33
	v_max_f32_e32 v33, v34, v34
	v_lshlrev_b64 v[36:37], 14, v[36:37]
	v_max_f32_e32 v32, 0, v32
	v_max_f32_e32 v33, 0, v33
	v_max_f32_e32 v34, v35, v35
	v_lshl_add_u64 v[36:37], s[2:3], 0, v[36:37]
	v_max_f32_e32 v39, 0, v34
	v_pk_mul_f32 v[32:33], v[32:33], v[32:33]
	v_lshl_add_u64 v[34:35], v[36:37], 0, v[106:107]
	v_pk_mul_f32 v[36:37], v[38:39], v[38:39]
; DEVI u32 pack2(float a, float b) { return f2bf(a) | (f2bf(b) << 16); }
;     ...
; #pragma unroll
;     for (int i = 0; i < 8; ++i) {
;       const int row = m0 + wm * 128 + i * 16 + l15;
; #pragma unroll
;       for (int j = 0; j < 4; ++j) {
;         const int n = n0 + wn * 64 + j * 16 + quad * 4;
;         f32x4 a = acc[i][j];
;         if (EPI == EPI_Z) {
;           u16* dst;
;           if (n0 < 1536) dst = (u16*)(p.ws + W_ZA) + (size_t)row * LZA + n;
;           else if (n0 < 4736) dst = (u16*)(p.ws + W_ZB) + (size_t)row * LZB + (n - 1536);
;           else dst = (u16*)(p.ws + W_ZC) + (size_t)row * LZC + (n - 4736);
;           *(uint2*)dst = make_uint2(pack2(a[0], a[1]), pack2(a[2], a[3]));
;         } else if (EPI == EPI_RES) {
;           if (split) {
;             float* op = p.out + (size_t)row * D + n;
;             unsafeAtomicAdd(op, a[0]); unsafeAtomicAdd(op + 1, a[1]); unsafeAtomicAdd(op + 2, a[2]); unsafeAtomicAdd(op + 3, a[3]);
;           } else {
;             const float* xin = res_from_input ? xrow_in(p, 0, row) : p.out + (size_t)row * D;
;             float4 xv = *(const float4*)(xin + n);
;             float4 o = make_float4(xv.x + a[0], xv.y + a[1], xv.z + a[2], xv.w + a[3]);
;             *(float4*)(p.out + (size_t)row * D + n) = o;
;           }
;         } else {
;           float r0 = fmaxf(a[0], 0.f), r1 = fmaxf(a[1], 0.f), r2 = fmaxf(a[2], 0.f), r3 = fmaxf(a[3], 0.f);
;           u16* dst = (u16*)(p.ws + W_H) + (size_t)row * DFF + n;
;           *(uint2*)dst = make_uint2(pack2(r0 * r0, r1 * r1), pack2(r2 * r2, r3 * r3));
;         }
	v_and_b32_sdwa v38, v33, v202 dst_sel:DWORD dst_unused:UNUSED_PAD src0_sel:WORD_1 src1_sel:DWORD
	v_and_b32_sdwa v39, v32, v202 dst_sel:DWORD dst_unused:UNUSED_PAD src0_sel:WORD_1 src1_sel:DWORD
	v_add3_u32 v32, v32, v39, s33
	v_add3_u32 v33, v33, v38, s33
	v_and_b32_sdwa v38, v37, v202 dst_sel:DWORD dst_unused:UNUSED_PAD src0_sel:WORD_1 src1_sel:DWORD
	v_and_b32_sdwa v39, v36, v202 dst_sel:DWORD dst_unused:UNUSED_PAD src0_sel:WORD_1 src1_sel:DWORD
	v_add3_u32 v37, v37, v38, s33
	v_add3_u32 v36, v36, v39, s33
	v_and_b32_e32 v37, 0xffff0000, v37
	v_and_b32_e32 v36, 0xffff0000, v36
	v_or_b32_sdwa v33, v37, v33 dst_sel:DWORD dst_unused:UNUSED_PAD src0_sel:DWORD src1_sel:WORD_1
	v_or_b32_sdwa v32, v36, v32 dst_sel:DWORD dst_unused:UNUSED_PAD src0_sel:DWORD src1_sel:WORD_1
	v_max_f32_e32 v29, v29, v29
	global_store_dwordx2 v[34:35], v[32:33], off
	v_max_f32_e32 v28, v28, v28
	v_max_f32_e32 v32, 0, v29
	v_max_f32_e32 v29, v30, v30
	v_max_f32_e32 v28, 0, v28
	v_max_f32_e32 v29, 0, v29
	v_max_f32_e32 v30, v31, v31
	v_max_f32_e32 v33, 0, v30
	v_pk_mul_f32 v[28:29], v[28:29], v[28:29]
	v_pk_mul_f32 v[30:31], v[32:33], v[32:33]
	v_and_b32_sdwa v32, v29, v202 dst_sel:DWORD dst_unused:UNUSED_PAD src0_sel:WORD_1 src1_sel:DWORD
	v_and_b32_sdwa v33, v28, v202 dst_sel:DWORD dst_unused:UNUSED_PAD src0_sel:WORD_1 src1_sel:DWORD
	v_add3_u32 v28, v28, v33, s33
	v_add3_u32 v29, v29, v32, s33
	v_and_b32_sdwa v32, v31, v202 dst_sel:DWORD dst_unused:UNUSED_PAD src0_sel:WORD_1 src1_sel:DWORD
	v_and_b32_sdwa v33, v30, v202 dst_sel:DWORD dst_unused:UNUSED_PAD src0_sel:WORD_1 src1_sel:DWORD
	v_add3_u32 v31, v31, v32, s33
	v_add3_u32 v30, v30, v33, s33
	v_and_b32_e32 v31, 0xffff0000, v31
	v_and_b32_e32 v30, 0xffff0000, v30
	v_or_b32_sdwa v29, v31, v29 dst_sel:DWORD dst_unused:UNUSED_PAD src0_sel:DWORD src1_sel:WORD_1
	v_or_b32_sdwa v28, v30, v28 dst_sel:DWORD dst_unused:UNUSED_PAD src0_sel:DWORD src1_sel:WORD_1
	v_max_f32_e32 v25, v25, v25
	global_store_dwordx2 v[34:35], v[28:29], off offset:32
	v_max_f32_e32 v24, v24, v24
	v_max_f32_e32 v28, 0, v25
	v_max_f32_e32 v25, v26, v26
	v_max_f32_e32 v24, 0, v24
	v_max_f32_e32 v25, 0, v25
	v_max_f32_e32 v26, v27, v27
	v_max_f32_e32 v29, 0, v26
	v_pk_mul_f32 v[24:25], v[24:25], v[24:25]
	v_pk_mul_f32 v[26:27], v[28:29], v[28:29]
	v_and_b32_sdwa v28, v25, v202 dst_sel:DWORD dst_unused:UNUSED_PAD src0_sel:WORD_1 src1_sel:DWORD
	v_and_b32_sdwa v29, v24, v202 dst_sel:DWORD dst_unused:UNUSED_PAD src0_sel:WORD_1 src1_sel:DWORD
	v_add3_u32 v24, v24, v29, s33
	v_add3_u32 v25, v25, v28, s33
	v_and_b32_sdwa v28, v27, v202 dst_sel:DWORD dst_unused:UNUSED_PAD src0_sel:WORD_1 src1_sel:DWORD
	v_and_b32_sdwa v29, v26, v202 dst_sel:DWORD dst_unused:UNUSED_PAD src0_sel:WORD_1 src1_sel:DWORD
	v_add3_u32 v27, v27, v28, s33
	v_add3_u32 v26, v26, v29, s33
	v_and_b32_e32 v27, 0xffff0000, v27
	v_and_b32_e32 v26, 0xffff0000, v26
	v_or_b32_sdwa v25, v27, v25 dst_sel:DWORD dst_unused:UNUSED_PAD src0_sel:DWORD src1_sel:WORD_1
	v_or_b32_sdwa v24, v26, v24 dst_sel:DWORD dst_unused:UNUSED_PAD src0_sel:DWORD src1_sel:WORD_1
	v_max_f32_e32 v21, v21, v21
	global_store_dwordx2 v[34:35], v[24:25], off offset:64
	v_max_f32_e32 v20, v20, v20
	v_max_f32_e32 v24, 0, v21
	v_max_f32_e32 v21, v22, v22
	v_max_f32_e32 v20, 0, v20
	v_max_f32_e32 v21, 0, v21
	v_max_f32_e32 v22, v23, v23
	v_max_f32_e32 v25, 0, v22
	v_pk_mul_f32 v[20:21], v[20:21], v[20:21]
	v_pk_mul_f32 v[22:23], v[24:25], v[24:25]
	v_and_b32_sdwa v24, v21, v202 dst_sel:DWORD dst_unused:UNUSED_PAD src0_sel:WORD_1 src1_sel:DWORD
	v_and_b32_sdwa v25, v20, v202 dst_sel:DWORD dst_unused:UNUSED_PAD src0_sel:WORD_1 src1_sel:DWORD
	v_add3_u32 v20, v20, v25, s33
	v_add3_u32 v21, v21, v24, s33
	v_and_b32_sdwa v24, v23, v202 dst_sel:DWORD dst_unused:UNUSED_PAD src0_sel:WORD_1 src1_sel:DWORD
	v_and_b32_sdwa v25, v22, v202 dst_sel:DWORD dst_unused:UNUSED_PAD src0_sel:WORD_1 src1_sel:DWORD
	v_add3_u32 v23, v23, v24, s33
	v_add3_u32 v22, v22, v25, s33
	v_and_b32_e32 v23, 0xffff0000, v23
	v_and_b32_e32 v22, 0xffff0000, v22
	v_or_b32_sdwa v21, v23, v21 dst_sel:DWORD dst_unused:UNUSED_PAD src0_sel:DWORD src1_sel:WORD_1
	v_or_b32_sdwa v20, v22, v20 dst_sel:DWORD dst_unused:UNUSED_PAD src0_sel:DWORD src1_sel:WORD_1
	global_store_dwordx2 v[34:35], v[20:21], off offset:96
	v_or_b32_e32 v20, 0x70, v104
	v_max_f32_e32 v17, v17, v17
	v_ashrrev_i32_e32 v21, 31, v20
	v_max_f32_e32 v16, v16, v16
	v_max_f32_e32 v22, 0, v17
	v_max_f32_e32 v17, v18, v18
	v_lshlrev_b64 v[20:21], 14, v[20:21]
; DEVI u32 pack2(float a, float b) { return f2bf(a) | (f2bf(b) << 16); }
;     ...
; #pragma unroll
;     for (int i = 0; i < 8; ++i) {
;       const int row = m0 + wm * 128 + i * 16 + l15;
; #pragma unroll
;       for (int j = 0; j < 4; ++j) {
;         const int n = n0 + wn * 64 + j * 16 + quad * 4;
;         f32x4 a = acc[i][j];
;         if (EPI == EPI_Z) {
;           u16* dst;
;           if (n0 < 1536) dst = (u16*)(p.ws + W_ZA) + (size_t)row * LZA + n;
;           else if (n0 < 4736) dst = (u16*)(p.ws + W_ZB) + (size_t)row * LZB + (n - 1536);
;           else dst = (u16*)(p.ws + W_ZC) + (size_t)row * LZC + (n - 4736);
;           *(uint2*)dst = make_uint2(pack2(a[0], a[1]), pack2(a[2], a[3]));
;         } else if (EPI == EPI_RES) {
;           if (split) {
;             float* op = p.out + (size_t)row * D + n;
;             unsafeAtomicAdd(op, a[0]); unsafeAtomicAdd(op + 1, a[1]); unsafeAtomicAdd(op + 2, a[2]); unsafeAtomicAdd(op + 3, a[3]);
;           } else {
;             const float* xin = res_from_input ? xrow_in(p, 0, row) : p.out + (size_t)row * D;
;             float4 xv = *(const float4*)(xin + n);
;             float4 o = make_float4(xv.x + a[0], xv.y + a[1], xv.z + a[2], xv.w + a[3]);
;             *(float4*)(p.out + (size_t)row * D + n) = o;
;           }
;         } else {
;           float r0 = fmaxf(a[0], 0.f), r1 = fmaxf(a[1], 0.f), r2 = fmaxf(a[2], 0.f), r3 = fmaxf(a[3], 0.f);
;           u16* dst = (u16*)(p.ws + W_H) + (size_t)row * DFF + n;
;           *(uint2*)dst = make_uint2(pack2(r0 * r0, r1 * r1), pack2(r2 * r2, r3 * r3));
;         }
	v_max_f32_e32 v16, 0, v16
	v_max_f32_e32 v17, 0, v17
	v_max_f32_e32 v18, v19, v19
	v_lshl_add_u64 v[20:21], s[2:3], 0, v[20:21]
	v_max_f32_e32 v23, 0, v18
	v_pk_mul_f32 v[16:17], v[16:17], v[16:17]
	v_lshl_add_u64 v[18:19], v[20:21], 0, v[106:107]
	v_pk_mul_f32 v[20:21], v[22:23], v[22:23]
	v_and_b32_sdwa v22, v17, v202 dst_sel:DWORD dst_unused:UNUSED_PAD src0_sel:WORD_1 src1_sel:DWORD
	v_and_b32_sdwa v23, v16, v202 dst_sel:DWORD dst_unused:UNUSED_PAD src0_sel:WORD_1 src1_sel:DWORD
	v_add3_u32 v16, v16, v23, s33
	v_add3_u32 v17, v17, v22, s33
	v_and_b32_sdwa v22, v21, v202 dst_sel:DWORD dst_unused:UNUSED_PAD src0_sel:WORD_1 src1_sel:DWORD
	v_and_b32_sdwa v23, v20, v202 dst_sel:DWORD dst_unused:UNUSED_PAD src0_sel:WORD_1 src1_sel:DWORD
	v_add3_u32 v21, v21, v22, s33
	v_add3_u32 v20, v20, v23, s33
	v_and_b32_e32 v21, 0xffff0000, v21
	v_and_b32_e32 v20, 0xffff0000, v20
	v_or_b32_sdwa v17, v21, v17 dst_sel:DWORD dst_unused:UNUSED_PAD src0_sel:DWORD src1_sel:WORD_1
	v_or_b32_sdwa v16, v20, v16 dst_sel:DWORD dst_unused:UNUSED_PAD src0_sel:DWORD src1_sel:WORD_1
	v_max_f32_e32 v13, v13, v13
	global_store_dwordx2 v[18:19], v[16:17], off
	v_max_f32_e32 v12, v12, v12
	v_max_f32_e32 v16, 0, v13
	v_max_f32_e32 v13, v14, v14
	v_max_f32_e32 v12, 0, v12
	v_max_f32_e32 v13, 0, v13
	v_max_f32_e32 v14, v15, v15
	v_max_f32_e32 v17, 0, v14
	v_pk_mul_f32 v[12:13], v[12:13], v[12:13]
	v_pk_mul_f32 v[14:15], v[16:17], v[16:17]
	v_and_b32_sdwa v16, v13, v202 dst_sel:DWORD dst_unused:UNUSED_PAD src0_sel:WORD_1 src1_sel:DWORD
	v_and_b32_sdwa v17, v12, v202 dst_sel:DWORD dst_unused:UNUSED_PAD src0_sel:WORD_1 src1_sel:DWORD
	v_add3_u32 v12, v12, v17, s33
	v_add3_u32 v13, v13, v16, s33
	v_and_b32_sdwa v16, v15, v202 dst_sel:DWORD dst_unused:UNUSED_PAD src0_sel:WORD_1 src1_sel:DWORD
	v_and_b32_sdwa v17, v14, v202 dst_sel:DWORD dst_unused:UNUSED_PAD src0_sel:WORD_1 src1_sel:DWORD
	v_add3_u32 v15, v15, v16, s33
	v_add3_u32 v14, v14, v17, s33
	v_and_b32_e32 v15, 0xffff0000, v15
	v_and_b32_e32 v14, 0xffff0000, v14
	v_or_b32_sdwa v13, v15, v13 dst_sel:DWORD dst_unused:UNUSED_PAD src0_sel:DWORD src1_sel:WORD_1
	v_or_b32_sdwa v12, v14, v12 dst_sel:DWORD dst_unused:UNUSED_PAD src0_sel:DWORD src1_sel:WORD_1
	v_max_f32_e32 v9, v9, v9
	global_store_dwordx2 v[18:19], v[12:13], off offset:32
	v_max_f32_e32 v8, v8, v8
	v_max_f32_e32 v12, 0, v9
	v_max_f32_e32 v9, v10, v10
	v_max_f32_e32 v8, 0, v8
	v_max_f32_e32 v9, 0, v9
	v_max_f32_e32 v10, v11, v11
	v_max_f32_e32 v13, 0, v10
	v_pk_mul_f32 v[8:9], v[8:9], v[8:9]
	v_pk_mul_f32 v[10:11], v[12:13], v[12:13]
	v_and_b32_sdwa v12, v9, v202 dst_sel:DWORD dst_unused:UNUSED_PAD src0_sel:WORD_1 src1_sel:DWORD
	v_and_b32_sdwa v13, v8, v202 dst_sel:DWORD dst_unused:UNUSED_PAD src0_sel:WORD_1 src1_sel:DWORD
	v_add3_u32 v8, v8, v13, s33
	v_add3_u32 v9, v9, v12, s33
	v_and_b32_sdwa v12, v11, v202 dst_sel:DWORD dst_unused:UNUSED_PAD src0_sel:WORD_1 src1_sel:DWORD
	v_and_b32_sdwa v13, v10, v202 dst_sel:DWORD dst_unused:UNUSED_PAD src0_sel:WORD_1 src1_sel:DWORD
	v_add3_u32 v11, v11, v12, s33
	v_add3_u32 v10, v10, v13, s33
	v_and_b32_e32 v11, 0xffff0000, v11
	v_and_b32_e32 v10, 0xffff0000, v10
	v_or_b32_sdwa v9, v11, v9 dst_sel:DWORD dst_unused:UNUSED_PAD src0_sel:DWORD src1_sel:WORD_1
	v_or_b32_sdwa v8, v10, v8 dst_sel:DWORD dst_unused:UNUSED_PAD src0_sel:DWORD src1_sel:WORD_1
	v_max_f32_e32 v5, v5, v5
	global_store_dwordx2 v[18:19], v[8:9], off offset:64
	v_max_f32_e32 v4, v4, v4
	v_max_f32_e32 v8, 0, v5
	v_max_f32_e32 v5, v6, v6
	v_max_f32_e32 v4, 0, v4
	v_max_f32_e32 v5, 0, v5
	v_max_f32_e32 v6, v7, v7
	v_max_f32_e32 v9, 0, v6
	v_pk_mul_f32 v[4:5], v[4:5], v[4:5]
	v_pk_mul_f32 v[6:7], v[8:9], v[8:9]
	v_and_b32_sdwa v8, v5, v202 dst_sel:DWORD dst_unused:UNUSED_PAD src0_sel:WORD_1 src1_sel:DWORD
	v_and_b32_sdwa v9, v4, v202 dst_sel:DWORD dst_unused:UNUSED_PAD src0_sel:WORD_1 src1_sel:DWORD
	v_add3_u32 v4, v4, v9, s33
	v_add3_u32 v5, v5, v8, s33
	v_and_b32_sdwa v8, v7, v202 dst_sel:DWORD dst_unused:UNUSED_PAD src0_sel:WORD_1 src1_sel:DWORD
	v_and_b32_sdwa v9, v6, v202 dst_sel:DWORD dst_unused:UNUSED_PAD src0_sel:WORD_1 src1_sel:DWORD
	v_add3_u32 v7, v7, v8, s33
	v_add3_u32 v6, v6, v9, s33
	v_and_b32_e32 v7, 0xffff0000, v7
	v_and_b32_e32 v6, 0xffff0000, v6
	v_or_b32_sdwa v5, v7, v5 dst_sel:DWORD dst_unused:UNUSED_PAD src0_sel:DWORD src1_sel:WORD_1
	v_or_b32_sdwa v4, v6, v4 dst_sel:DWORD dst_unused:UNUSED_PAD src0_sel:DWORD src1_sel:WORD_1
	global_store_dwordx2 v[18:19], v[4:5], off offset:96
	s_branch .LBB0_1456

; DEVI int TID() { int t = threadIdx.x; asm volatile("" : "+v"(t)); return t; }
;   const int tid = TID(), lane = tid & 63, wave = tid >> 6;
;   const int l15 = lane & 15, quad = lane >> 4;
;   const int wm = wave >> 1, wn = wave & 1;
;   const int TM = KS > 0 ? 128 : NTOK / 256;
;   const int total = TM * TN + (KS > 0 ? TN * KS : 0);
;   const int nkfull = K / 32;
;   const int ldrow = tid >> 2, ldp = tid & 3;
;   const int lsw = ((ldp ^ ((ldrow >> 2) & 3)) * 16);
;   const int rsw = ((quad ^ ((l15 >> 2) & 3)) * 16);
;   const int nfullp = TN >> 3;
;     ...
;     const u16* Ag = A + (size_t)(m0 + ldrow) * K + ldp * 8 + kt0 * 32;
;     const u16* Bg = Bt + (size_t)(n0 + ldrow) * K + ldp * 8 + kt0 * 32;
.LBB0_1471:
	s_or_b64 exec, exec, s[2:3]
	v_mov_b32_e32 v6, v1
	s_barrier
	v_readlane_b32 s2, v251, 60
	v_lshrrev_b32_e32 v4, 4, v6
	v_lshrrev_b32_e32 v9, 2, v6
	v_xor_b32_e32 v4, v4, v9
	v_lshlrev_b32_e32 v5, 4, v6
	v_lshlrev_b32_e32 v4, 4, v4
	v_bitop3_b32 v8, v5, 48, v6 bitop3:0x48
	v_and_b32_e32 v10, 48, v4
	v_and_b32_e32 v4, 48, v5
	v_mov_b32_e32 v5, v2
	v_readlane_b32 s3, v251, 61
	v_ashrrev_i32_e32 v3, 2, v6
	v_bfe_u32 v7, v6, 6, 1
	v_lshl_add_u64 v[132:133], s[2:3], 0, v[4:5]
	v_readlane_b32 s2, v253, 14
	v_readlane_b32 s3, v253, 15
	v_add_u32_e32 v8, 0, v8
	v_and_b32_e32 v144, 0xffffff8f, v6
	v_lshl_add_u64 v[134:135], s[2:3], 0, v[4:5]
	v_lshlrev_b32_e32 v4, 6, v3
	v_and_b32_e32 v5, 12, v9
	v_lshl_or_b32 v145, v7, 6, v5
	v_lshlrev_b32_e32 v5, 6, v6
	v_add_u32_e32 v150, v8, v4
	v_and_b32_e32 v4, 3, v6
	v_readlane_b32 s2, v251, 1
	v_and_b32_e32 v147, 0x3c0, v5
	v_and_b32_e32 v148, 0xffffe3c0, v5
	v_lshlrev_b32_e32 v4, 4, v4
	v_mov_b32_e32 v5, v2
	v_readlane_b32 s3, v251, 2
	v_lshlrev_b32_e32 v146, 12, v7
	v_add_u32_e32 v149, 0, v10
	v_lshl_add_u64 v[136:137], s[2:3], 0, v[4:5]
	s_mov_b32 s2, 0
	s_mov_b32 s8, 0
	v_writelane_b32 v255, s20, 41
	v_writelane_b32 v255, s21, 42
	v_writelane_b32 v255, s22, 43
	v_writelane_b32 v255, s23, 44
	v_lshrrev_b32_e32 v4, 6, v1
	v_lshrrev_b32_e32 v5, 4, v1
	v_xor_b32_e32 v5, v5, v1
	v_readfirstlane_b32 s20, v4
	v_and_b32_e32 v5, 3, v5
	v_and_b32_e32 v4, 3, v1
	v_sub_u32_e32 v4, v5, v4
	v_lshlrev_b32_e32 v4, 4, v4
	v_ashrrev_i32_e32 v5, 31, v4
	s_lshl_b32 s20, s20, 10
	v_lshl_add_u64 v[132:133], v[132:133], 0, v[4:5]
	v_lshl_add_u64 v[134:135], v[134:135], 0, v[4:5]
	v_lshl_add_u64 v[136:137], v[136:137], 0, v[4:5]
	s_branch .LBB0_1473

;     ...
;   for (int rnd = 0; rnd * nb < total; ++rnd) {
;     const int id = rnd * nb + (bid & 7) * (nb >> 3) + (bid >> 3);
;     if (id >= total) continue;
;     int tm, tn;
;     int kt0 = 0, nk = nkfull;
;     bool split = false;
;     if (id >= TM * TN) {
;       const int piece = id - TM * TN;
;       tn = piece / KS;
;       const int ks = piece - tn * KS;
;       tm = 128;
;       nk = nkfull / KS;
;       kt0 = ks * nk;
;       split = true;
;     } else {
;       const int pan = id / (TM * 8);
;       if (pan < nfullp) {
;         const int r = id - pan * (TM * 8);
;         tm = r >> 3; tn = pan * 8 + (r & 7);
;       } else {
;         const int pw = TN - nfullp * 8;
;         const int r = id - nfullp * (TM * 8);
;         tm = r / pw; tn = nfullp * 8 + r % pw;
;       }
;     }
;     const int m0 = tm * 256, n0 = tn * 128;
;     f32x4 acc[8][4];
; #pragma unroll
;     for (int i = 0; i < 8; ++i)
; #pragma unroll
;       for (int j = 0; j < 4; ++j) acc[i][j] = f32x4{0.f, 0.f, 0.f, 0.f};
;     u32x4 ra[4], rb[2];
;     const u16* Ag = A + (size_t)(m0 + ldrow) * K + ldp * 8 + kt0 * 32;
;     const u16* Bg = Bt + (size_t)(n0 + ldrow) * K + ldp * 8 + kt0 * 32;
; #pragma unroll
;     for (int i = 0; i < 4; ++i) ra[i] = *(const u32x4*)(Ag + (size_t)(i * 64) * K);
; #pragma unroll
;     for (int i = 0; i < 2; ++i) rb[i] = *(const u32x4*)(Bg + (size_t)(i * 64) * K);
;     __syncthreads();
; #pragma unroll
;     for (int i = 0; i < 4; ++i) *(u32x4*)(smem + (ldrow + i * 64) * 64 + lsw) = ra[i];
; #pragma unroll
;     for (int i = 0; i < 2; ++i) *(u32x4*)(smem + 16384 + (ldrow + i * 64) * 64 + lsw) = rb[i];
;     __syncthreads();
.LBB0_1478:
	v_add_u32_e32 v4, s9, v3
	v_ashrrev_i32_e32 v5, 31, v4
	s_waitcnt vmcnt(3)
	v_lshlrev_b64 v[64:65], 14, v[4:5]
	v_lshl_add_u64 v[4:5], v[132:133], 0, v[64:65]
	s_lshl_b64 s[6:7], s[6:7], 1
	v_lshl_add_u64 v[4:5], v[4:5], 0, s[6:7]
	v_add_co_u32_e32 v8, vcc, s17, v4
	s_lshl_b32 s10, s11, 7
	s_nop 0
	v_addc_co_u32_e32 v9, vcc, 0, v5, vcc
	v_add_u32_e32 v6, s10, v3
	s_barrier
	s_mov_b32 m0, s20
	s_nop 0
	global_load_lds_dwordx4 v[4:5], off
	s_add_u32 m0, s20, 0x5fc0
	s_nop 0
	global_load_lds_dwordx4 v[4:5], off offset:64
	s_add_u32 m0, s20, 0x1000
	s_nop 0
	global_load_lds_dwordx4 v[8:9], off
	s_add_u32 m0, s20, 0x6fc0
	s_nop 0
	global_load_lds_dwordx4 v[8:9], off offset:64
	v_add_co_u32_e32 v8, vcc, s18, v4
	v_ashrrev_i32_e32 v7, 31, v6
	s_nop 0
	v_addc_co_u32_e32 v9, vcc, 0, v5, vcc
	v_lshlrev_b64 v[66:67], 14, v[6:7]
	v_add_co_u32_e32 v4, vcc, s19, v4
	v_lshl_add_u64 v[6:7], v[134:135], 0, v[66:67]
	s_nop 0
	v_addc_co_u32_e32 v5, vcc, 0, v5, vcc
	s_add_u32 m0, s20, 0x2000
	s_nop 0
	global_load_lds_dwordx4 v[8:9], off
	s_add_u32 m0, s20, 0x7fc0
	s_nop 0
	global_load_lds_dwordx4 v[8:9], off offset:64
	s_add_u32 m0, s20, 0x3000
	s_nop 0
	global_load_lds_dwordx4 v[4:5], off
	s_add_u32 m0, s20, 0x8fc0
	s_nop 0
	global_load_lds_dwordx4 v[4:5], off offset:64
	v_lshl_add_u64 v[4:5], v[6:7], 0, s[6:7]
	v_add_co_u32_e32 v6, vcc, s17, v4
	v_lshl_add_u64 v[64:65], v[64:65], 0, s[6:7]
	s_nop 0
	v_addc_co_u32_e32 v7, vcc, 0, v5, vcc
	s_add_u32 m0, s20, 0x4000
	s_nop 0
	global_load_lds_dwordx4 v[4:5], off
	s_add_u32 m0, s20, 0x9fc0
	s_nop 0
	global_load_lds_dwordx4 v[4:5], off offset:64
	s_add_u32 m0, s20, 0x5000
	s_nop 0
	global_load_lds_dwordx4 v[6:7], off
	s_add_u32 m0, s20, 0xafc0
	s_nop 0
	global_load_lds_dwordx4 v[6:7], off offset:64
	s_lshl_b32 s12, s12, 6
	v_mov_b32_e32 v4, 0
	v_lshl_add_u64 v[138:139], v[136:137], 0, v[64:65]
	v_lshl_add_u64 v[64:65], v[66:67], 0, s[6:7]
	s_mov_b32 s11, 0
	s_add_u32 s12, s12, 0xc0
	v_mov_b32_e32 v5, v4
	v_mov_b32_e32 v6, v4
	v_mov_b32_e32 v7, v4
	v_mov_b32_e32 v8, v4
	v_mov_b32_e32 v9, v4
	v_mov_b32_e32 v10, v4
	v_mov_b32_e32 v11, v4
	v_mov_b32_e32 v12, v4
	v_mov_b32_e32 v13, v4
	v_mov_b32_e32 v14, v4
	v_mov_b32_e32 v15, v4
	v_mov_b32_e32 v16, v4
	v_mov_b32_e32 v17, v4
	v_mov_b32_e32 v18, v4
	v_mov_b32_e32 v19, v4
	v_mov_b32_e32 v20, v4
	v_mov_b32_e32 v21, v4
	v_mov_b32_e32 v22, v4
	v_mov_b32_e32 v23, v4
	v_mov_b32_e32 v24, v4
	v_mov_b32_e32 v25, v4
	v_mov_b32_e32 v26, v4
	v_mov_b32_e32 v27, v4
	v_mov_b32_e32 v28, v4
	v_mov_b32_e32 v29, v4
	v_mov_b32_e32 v30, v4
	v_mov_b32_e32 v31, v4
	v_mov_b32_e32 v32, v4
	v_mov_b32_e32 v33, v4
	v_mov_b32_e32 v34, v4
	v_mov_b32_e32 v35, v4
	v_mov_b32_e32 v36, v4
	v_mov_b32_e32 v37, v4
	v_mov_b32_e32 v38, v4
	v_lshl_add_u64 v[140:141], v[136:137], 0, v[64:65]
	v_mov_b32_e32 v39, v4
	v_mov_b32_e32 v64, v4
	v_mov_b32_e32 v65, v4
	v_mov_b32_e32 v66, v4
	v_mov_b32_e32 v67, v4
	v_mov_b32_e32 v68, v4
	v_mov_b32_e32 v69, v4
	v_mov_b32_e32 v70, v4
	v_mov_b32_e32 v71, v4
	v_mov_b32_e32 v72, v4
	v_mov_b32_e32 v73, v4
	v_mov_b32_e32 v74, v4
	v_mov_b32_e32 v75, v4
	v_mov_b32_e32 v76, v4
	v_mov_b32_e32 v77, v4
	v_mov_b32_e32 v78, v4
	v_mov_b32_e32 v79, v4
	v_mov_b32_e32 v40, v4
	v_mov_b32_e32 v41, v4
	v_mov_b32_e32 v42, v4
	v_mov_b32_e32 v43, v4
	v_mov_b32_e32 v44, v4
	v_mov_b32_e32 v45, v4
	v_mov_b32_e32 v46, v4
	v_mov_b32_e32 v47, v4
	v_mov_b32_e32 v48, v4
	v_mov_b32_e32 v49, v4
	v_mov_b32_e32 v50, v4
	v_mov_b32_e32 v51, v4
	v_mov_b32_e32 v52, v4
	v_mov_b32_e32 v53, v4
	v_mov_b32_e32 v54, v4
	v_mov_b32_e32 v55, v4
	v_mov_b32_e32 v56, v4
	v_mov_b32_e32 v57, v4
	v_mov_b32_e32 v58, v4
	v_mov_b32_e32 v59, v4
	v_mov_b32_e32 v60, v4
	v_mov_b32_e32 v61, v4
	v_mov_b32_e32 v62, v4
	v_mov_b32_e32 v63, v4
	v_mov_b32_e32 v80, v4
	v_mov_b32_e32 v81, v4
	v_mov_b32_e32 v82, v4
	v_mov_b32_e32 v83, v4
	v_mov_b32_e32 v84, v4
	v_mov_b32_e32 v85, v4
	v_mov_b32_e32 v86, v4
	v_mov_b32_e32 v87, v4
	v_mov_b32_e32 v88, v4
	v_mov_b32_e32 v89, v4
	v_mov_b32_e32 v90, v4
	v_mov_b32_e32 v91, v4
	v_mov_b32_e32 v92, v4
	v_mov_b32_e32 v93, v4
	v_mov_b32_e32 v94, v4
	v_mov_b32_e32 v95, v4
	v_mov_b32_e32 v96, v4
	v_mov_b32_e32 v97, v4
	v_mov_b32_e32 v98, v4
	v_mov_b32_e32 v99, v4
	v_mov_b32_e32 v100, v4
	v_mov_b32_e32 v101, v4
	v_mov_b32_e32 v102, v4
	v_mov_b32_e32 v103, v4
	v_mov_b32_e32 v104, v4
	v_mov_b32_e32 v105, v4
	v_mov_b32_e32 v106, v4
	v_mov_b32_e32 v107, v4
	v_mov_b32_e32 v108, v4
	v_mov_b32_e32 v109, v4
	v_mov_b32_e32 v110, v4
	v_mov_b32_e32 v111, v4
	v_mov_b32_e32 v112, v4
	v_mov_b32_e32 v113, v4
	v_mov_b32_e32 v114, v4
	v_mov_b32_e32 v115, v4
	v_mov_b32_e32 v116, v4
	v_mov_b32_e32 v117, v4
	v_mov_b32_e32 v118, v4
	v_mov_b32_e32 v119, v4
	v_mov_b32_e32 v120, v4
	v_mov_b32_e32 v121, v4
	v_mov_b32_e32 v122, v4
	v_mov_b32_e32 v123, v4
	v_mov_b32_e32 v124, v4
	v_mov_b32_e32 v125, v4
	v_mov_b32_e32 v126, v4
	v_mov_b32_e32 v127, v4
	v_mov_b32_e32 v128, v4
	v_mov_b32_e32 v129, v4
	v_mov_b32_e32 v130, v4
	v_mov_b32_e32 v131, v4
	s_mov_b64 s[2:3], 0x80
	s_mov_b32 s21, 0
	s_mov_b32 s22, 0xc000
	s_waitcnt vmcnt(0) lgkmcnt(0)
	s_barrier
;     ...
;     for (int kt = 0; kt < nk; ++kt) {
;       const int buf = kt & 1;
;       if (kt + 1 < nk) {
; #pragma unroll
;         for (int i = 0; i < 4; ++i) ra[i] = *(const u32x4*)(Ag + (size_t)(i * 64) * K + (kt + 1) * 32);
; #pragma unroll
;         for (int i = 0; i < 2; ++i) rb[i] = *(const u32x4*)(Bg + (size_t)(i * 64) * K + (kt + 1) * 32);
;       }
;       const char* As = smem + buf * 24576;
;       const char* Bs = As + 16384;
;       bf16x8 bfr[4];
; #pragma unroll
;       for (int j = 0; j < 4; ++j) bfr[j] = *(const bf16x8*)(Bs + (wn * 64 + j * 16 + l15) * 64 + rsw);
;       bf16x8 afr[8];
; #pragma unroll
;       for (int i = 0; i < 8; ++i) afr[i] = *(const bf16x8*)(As + (wm * 128 + i * 16 + l15) * 64 + rsw);
;       __builtin_amdgcn_s_setprio(1);
; #pragma unroll
;       for (int i = 0; i < 8; ++i) {
; #pragma unroll
;         for (int j = 0; j < 4; ++j) acc[i][j] = __builtin_amdgcn_mfma_f32_16x16x32_bf16(bfr[j], afr[i], acc[i][j], 0, 0, 0);
;       }
;       __builtin_amdgcn_s_setprio(0);
;       if (kt + 1 < nk) {
;         char* Aw = smem + (buf ^ 1) * 24576;
;         char* Bw = Aw + 16384;
; #pragma unroll
;         for (int i = 0; i < 4; ++i) *(u32x4*)(Aw + (ldrow + i * 64) * 64 + lsw) = ra[i];
; #pragma unroll
;         for (int i = 0; i < 2; ++i) *(u32x4*)(Bw + (ldrow + i * 64) * 64 + lsw) = rb[i];
;       }
;       __syncthreads();
;     }
.LBB0_1479:
	s_add_u32 s23, s22, s20
	v_lshl_add_u64 v[142:143], v[138:139], 0, s[2:3]
	s_mov_b32 s6, 0xa580000
	v_add_co_u32_e32 v154, vcc, s6, v142
	s_mov_b32 s6, 0xa680000
	s_nop 0
	v_addc_co_u32_e32 v155, vcc, 0, v143, vcc
	v_add_co_u32_e32 v156, vcc, s6, v142
	s_mov_b32 s6, 0xa780000
	s_nop 0
	v_addc_co_u32_e32 v157, vcc, 0, v143, vcc
	v_add_co_u32_e32 v160, vcc, s6, v142
	s_mov_b32 s6, 0xa880000
	s_nop 0
	v_addc_co_u32_e32 v161, vcc, 0, v143, vcc
	v_add_co_u32_e32 v142, vcc, s6, v142
	v_lshl_add_u64 v[152:153], v[140:141], 0, s[2:3]
	s_nop 0
	v_addc_co_u32_e32 v143, vcc, 0, v143, vcc
	s_mov_b32 s6, 0x338b3000
	v_add_co_u32_e32 v168, vcc, s6, v152
	s_mov_b32 s6, 0x339b3000
	s_nop 0
	v_addc_co_u32_e32 v169, vcc, 0, v153, vcc
	v_add_co_u32_e32 v172, vcc, s6, v152
	s_and_b32 s6, s11, 1
	s_nop 0
	v_addc_co_u32_e32 v173, vcc, 0, v153, vcc
	s_mov_b32 m0, s23
	s_nop 0
	global_load_lds_dwordx4 v[154:155], off
	s_nop 0
	s_add_u32 m0, s23, 0x1000
	s_nop 0
	global_load_lds_dwordx4 v[156:157], off
	s_nop 0
	s_add_u32 m0, s23, 0x2000
	s_nop 0
	global_load_lds_dwordx4 v[160:161], off
	s_nop 0
	s_add_u32 m0, s23, 0x3000
	s_nop 0
	global_load_lds_dwordx4 v[142:143], off
	s_nop 0
	s_add_u32 m0, s23, 0x4000
	s_nop 0
	global_load_lds_dwordx4 v[168:169], off
	s_nop 0
	s_add_u32 m0, s23, 0x5000
	s_nop 0
	global_load_lds_dwordx4 v[172:173], off
	v_add_u32_e32 v142, s21, v149
	v_add3_u32 v143, v142, v146, v147
	v_add_u32_e32 v142, v142, v148
	ds_read_b128 v[176:179], v143 offset:16384
	ds_read_b128 v[180:183], v143 offset:17408
	ds_read_b128 v[184:187], v143 offset:18432
	ds_read_b128 v[188:191], v143 offset:19456
	ds_read_b128 v[192:195], v142
	ds_read_b128 v[196:199], v142 offset:1024
	ds_read_b128 v[210:213], v142 offset:2048
	ds_read_b128 v[220:223], v142 offset:3072
	ds_read_b128 v[224:227], v142 offset:4096
	ds_read_b128 v[230:233], v142 offset:5120
	ds_read_b128 v[234:237], v142 offset:6144
	ds_read_b128 v[238:241], v142 offset:7168
	s_add_i32 s11, s11, 1
	s_setprio 1
	s_waitcnt lgkmcnt(7)
	v_mfma_f32_16x16x32_bf16 v[128:131], v[176:179], v[192:195], v[128:131]
	v_mfma_f32_16x16x32_bf16 v[124:127], v[180:183], v[192:195], v[124:127]
	v_mfma_f32_16x16x32_bf16 v[120:123], v[184:187], v[192:195], v[120:123]
	v_mfma_f32_16x16x32_bf16 v[116:119], v[188:191], v[192:195], v[116:119]
	s_waitcnt lgkmcnt(6)
	v_mfma_f32_16x16x32_bf16 v[112:115], v[176:179], v[196:199], v[112:115]
	v_mfma_f32_16x16x32_bf16 v[108:111], v[180:183], v[196:199], v[108:111]
	v_mfma_f32_16x16x32_bf16 v[104:107], v[184:187], v[196:199], v[104:107]
	v_mfma_f32_16x16x32_bf16 v[100:103], v[188:191], v[196:199], v[100:103]
	s_waitcnt lgkmcnt(5)
	v_mfma_f32_16x16x32_bf16 v[96:99], v[176:179], v[210:213], v[96:99]
	v_mfma_f32_16x16x32_bf16 v[92:95], v[180:183], v[210:213], v[92:95]
	v_mfma_f32_16x16x32_bf16 v[88:91], v[184:187], v[210:213], v[88:91]
	v_mfma_f32_16x16x32_bf16 v[84:87], v[188:191], v[210:213], v[84:87]
	s_waitcnt lgkmcnt(4)
	v_mfma_f32_16x16x32_bf16 v[80:83], v[176:179], v[220:223], v[80:83]
	v_mfma_f32_16x16x32_bf16 v[76:79], v[180:183], v[220:223], v[76:79]
	v_mfma_f32_16x16x32_bf16 v[72:75], v[184:187], v[220:223], v[72:75]
	v_mfma_f32_16x16x32_bf16 v[68:71], v[188:191], v[220:223], v[68:71]
	s_waitcnt lgkmcnt(3)
	v_mfma_f32_16x16x32_bf16 v[64:67], v[176:179], v[224:227], v[64:67]
	v_mfma_f32_16x16x32_bf16 v[60:63], v[180:183], v[224:227], v[60:63]
	v_mfma_f32_16x16x32_bf16 v[56:59], v[184:187], v[224:227], v[56:59]
	v_mfma_f32_16x16x32_bf16 v[52:55], v[188:191], v[224:227], v[52:55]
	s_waitcnt lgkmcnt(2)
	v_mfma_f32_16x16x32_bf16 v[48:51], v[176:179], v[230:233], v[48:51]
	v_mfma_f32_16x16x32_bf16 v[44:47], v[180:183], v[230:233], v[44:47]
	v_mfma_f32_16x16x32_bf16 v[40:43], v[184:187], v[230:233], v[40:43]
	v_mfma_f32_16x16x32_bf16 v[36:39], v[188:191], v[230:233], v[36:39]
	s_waitcnt lgkmcnt(1)
	v_mfma_f32_16x16x32_bf16 v[32:35], v[176:179], v[234:237], v[32:35]
	v_mfma_f32_16x16x32_bf16 v[28:31], v[180:183], v[234:237], v[28:31]
	v_mfma_f32_16x16x32_bf16 v[24:27], v[184:187], v[234:237], v[24:27]
	v_mfma_f32_16x16x32_bf16 v[20:23], v[188:191], v[234:237], v[20:23]
	s_waitcnt lgkmcnt(0)
	v_mfma_f32_16x16x32_bf16 v[16:19], v[176:179], v[238:241], v[16:19]
	v_mfma_f32_16x16x32_bf16 v[12:15], v[180:183], v[238:241], v[12:15]
	v_mfma_f32_16x16x32_bf16 v[8:11], v[184:187], v[238:241], v[8:11]
	v_mfma_f32_16x16x32_bf16 v[4:7], v[188:191], v[238:241], v[4:7]
	s_setprio 0
	s_add_u32 s2, s2, 64
	s_addc_u32 s3, s3, 0
	s_add_u32 s21, s21, 0x6000
	s_cmp_eq_u32 s21, 0x12000
	s_cselect_b32 s21, 0, s21
	s_add_u32 s22, s22, 0x6000
	s_cmp_eq_u32 s22, 0x12000
	s_cselect_b32 s22, 0, s22
	s_cmp_eq_u32 s12, s2
	s_waitcnt vmcnt(6)
	s_barrier
; DEVI u32 pack2(float a, float b) { return f2bf(a) | (f2bf(b) << 16); }
;     ...
;       const char* As = smem + buf * 24576;
;       const char* Bs = As + 16384;
;       bf16x8 bfr[4];
; #pragma unroll
;       for (int j = 0; j < 4; ++j) bfr[j] = *(const bf16x8*)(Bs + (wn * 64 + j * 16 + l15) * 64 + rsw);
;       bf16x8 afr[8];
; #pragma unroll
;       for (int i = 0; i < 8; ++i) afr[i] = *(const bf16x8*)(As + (wm * 128 + i * 16 + l15) * 64 + rsw);
;       __builtin_amdgcn_s_setprio(1);
; #pragma unroll
;       for (int i = 0; i < 8; ++i) {
; #pragma unroll
;         for (int j = 0; j < 4; ++j) acc[i][j] = __builtin_amdgcn_mfma_f32_16x16x32_bf16(bfr[j], afr[i], acc[i][j], 0, 0, 0);
;       }
;       __builtin_amdgcn_s_setprio(0);
;       if (kt + 1 < nk) {
;         char* Aw = smem + (buf ^ 1) * 24576;
;         char* Bw = Aw + 16384;
; #pragma unroll
;         for (int i = 0; i < 4; ++i) *(u32x4*)(Aw + (ldrow + i * 64) * 64 + lsw) = ra[i];
; #pragma unroll
;         for (int i = 0; i < 2; ++i) *(u32x4*)(Bw + (ldrow + i * 64) * 64 + lsw) = rb[i];
;       }
;       __syncthreads();
;     }
; #pragma unroll
;     for (int i = 0; i < 8; ++i) {
;       const int row = m0 + wm * 128 + i * 16 + l15;
; #pragma unroll
;       for (int j = 0; j < 4; ++j) {
;         const int n = n0 + wn * 64 + j * 16 + quad * 4;
;         f32x4 a = acc[i][j];
;         if (EPI == EPI_Z) {
;           u16* dst;
;           if (n0 < 1536) dst = (u16*)(p.ws + W_ZA) + (size_t)row * LZA + n;
;           else if (n0 < 4736) dst = (u16*)(p.ws + W_ZB) + (size_t)row * LZB + (n - 1536);
;           else dst = (u16*)(p.ws + W_ZC) + (size_t)row * LZC + (n - 4736);
;           *(uint2*)dst = make_uint2(pack2(a[0], a[1]), pack2(a[2], a[3]));
;         } else if (EPI == EPI_RES) {
;           if (split) {
;             float* op = p.out + (size_t)row * D + n;
;             unsafeAtomicAdd(op, a[0]); unsafeAtomicAdd(op + 1, a[1]); unsafeAtomicAdd(op + 2, a[2]); unsafeAtomicAdd(op + 3, a[3]);
;           } else {
;             const float* xin = res_from_input ? xrow_in(p, 0, row) : p.out + (size_t)row * D;
;             float4 xv = *(const float4*)(xin + n);
;             float4 o = make_float4(xv.x + a[0], xv.y + a[1], xv.z + a[2], xv.w + a[3]);
;             *(float4*)(p.out + (size_t)row * D + n) = o;
	s_cbranch_scc0 .LBB0_1479
	v_add_u32_e32 v142, s21, v149
	v_add3_u32 v143, v142, v146, v147
	v_add_u32_e32 v142, v142, v148
	ds_read_b128 v[138:141], v143 offset:16384
	ds_read_b128 v[152:155], v143 offset:17408
	ds_read_b128 v[156:159], v143 offset:18432
	ds_read_b128 v[160:163], v143 offset:19456
	ds_read_b128 v[164:167], v142
	ds_read_b128 v[168:171], v142 offset:1024
	ds_read_b128 v[172:175], v142 offset:2048
	ds_read_b128 v[176:179], v142 offset:3072
	ds_read_b128 v[180:183], v142 offset:4096
	ds_read_b128 v[184:187], v142 offset:5120
	ds_read_b128 v[188:191], v142 offset:6144
	ds_read_b128 v[192:195], v142 offset:7168
	s_setprio 1
	s_waitcnt lgkmcnt(7)
	v_mfma_f32_16x16x32_bf16 v[128:131], v[138:141], v[164:167], v[128:131]
	v_mfma_f32_16x16x32_bf16 v[124:127], v[152:155], v[164:167], v[124:127]
	v_mfma_f32_16x16x32_bf16 v[120:123], v[156:159], v[164:167], v[120:123]
	v_mfma_f32_16x16x32_bf16 v[116:119], v[160:163], v[164:167], v[116:119]
	s_waitcnt lgkmcnt(6)
	v_mfma_f32_16x16x32_bf16 v[112:115], v[138:141], v[168:171], v[112:115]
	v_mfma_f32_16x16x32_bf16 v[108:111], v[152:155], v[168:171], v[108:111]
	v_mfma_f32_16x16x32_bf16 v[104:107], v[156:159], v[168:171], v[104:107]
	v_mfma_f32_16x16x32_bf16 v[100:103], v[160:163], v[168:171], v[100:103]
	s_waitcnt lgkmcnt(5)
	v_mfma_f32_16x16x32_bf16 v[96:99], v[138:141], v[172:175], v[96:99]
	v_mfma_f32_16x16x32_bf16 v[92:95], v[152:155], v[172:175], v[92:95]
	v_mfma_f32_16x16x32_bf16 v[88:91], v[156:159], v[172:175], v[88:91]
	v_mfma_f32_16x16x32_bf16 v[84:87], v[160:163], v[172:175], v[84:87]
	s_waitcnt lgkmcnt(4)
	v_mfma_f32_16x16x32_bf16 v[80:83], v[138:141], v[176:179], v[80:83]
	v_mfma_f32_16x16x32_bf16 v[76:79], v[152:155], v[176:179], v[76:79]
	v_mfma_f32_16x16x32_bf16 v[72:75], v[156:159], v[176:179], v[72:75]
	v_mfma_f32_16x16x32_bf16 v[68:71], v[160:163], v[176:179], v[68:71]
	s_waitcnt lgkmcnt(3)
	v_mfma_f32_16x16x32_bf16 v[64:67], v[138:141], v[180:183], v[64:67]
	v_mfma_f32_16x16x32_bf16 v[60:63], v[152:155], v[180:183], v[60:63]
	v_mfma_f32_16x16x32_bf16 v[56:59], v[156:159], v[180:183], v[56:59]
	v_mfma_f32_16x16x32_bf16 v[52:55], v[160:163], v[180:183], v[52:55]
	s_waitcnt lgkmcnt(2)
	v_mfma_f32_16x16x32_bf16 v[48:51], v[138:141], v[184:187], v[48:51]
	v_mfma_f32_16x16x32_bf16 v[44:47], v[152:155], v[184:187], v[44:47]
	v_mfma_f32_16x16x32_bf16 v[40:43], v[156:159], v[184:187], v[40:43]
	v_mfma_f32_16x16x32_bf16 v[36:39], v[160:163], v[184:187], v[36:39]
	s_waitcnt lgkmcnt(1)
	v_mfma_f32_16x16x32_bf16 v[32:35], v[138:141], v[188:191], v[32:35]
	v_mfma_f32_16x16x32_bf16 v[28:31], v[152:155], v[188:191], v[28:31]
	v_mfma_f32_16x16x32_bf16 v[24:27], v[156:159], v[188:191], v[24:27]
	v_mfma_f32_16x16x32_bf16 v[20:23], v[160:163], v[188:191], v[20:23]
	s_waitcnt lgkmcnt(0)
	v_mfma_f32_16x16x32_bf16 v[16:19], v[138:141], v[192:195], v[16:19]
	v_mfma_f32_16x16x32_bf16 v[12:15], v[152:155], v[192:195], v[12:15]
	v_mfma_f32_16x16x32_bf16 v[8:11], v[156:159], v[192:195], v[8:11]
	v_mfma_f32_16x16x32_bf16 v[4:7], v[160:163], v[192:195], v[4:7]
	s_setprio 0
	s_waitcnt vmcnt(0)
	v_add_u32_e32 v140, s9, v144
	v_ashrrev_i32_e32 v141, 31, v140
	v_readlane_b32 s12, v253, 53
	v_or_b32_e32 v138, s10, v145
	v_lshlrev_b64 v[142:143], 13, v[140:141]
	v_readlane_b32 s14, v253, 55
	v_readlane_b32 s15, v253, 56
	v_ashrrev_i32_e32 v139, 31, v138
	s_mov_b64 s[2:3], -1
	v_lshl_add_u64 v[142:143], s[14:15], 0, v[142:143]
	v_lshl_add_u64 v[142:143], v[138:139], 2, v[142:143]
	s_and_b64 vcc, exec, s[4:5]
	s_barrier
	v_readlane_b32 s13, v253, 54
	s_cbranch_vccz .LBB0_1482
	global_load_dwordx4 v[152:155], v[142:143], off
	s_mov_b64 s[2:3], 0
	s_waitcnt vmcnt(0)
	v_pk_add_f32 v[152:153], v[128:129], v[152:153]
	v_pk_add_f32 v[154:155], v[130:131], v[154:155]
	global_store_dwordx4 v[142:143], v[152:155], off

; __global__ void __launch_bounds__(256, 2) mega(Params p) {
;     ...
;     gemm_phase<EPI_RES>(p, l, (const u16*)(p.ws + W_H), (const u16*)(p.ws + W_WTDN), DFF, D / 128, smem, bid, nb, false, 8);
;     grid.sync();
.LBB0_1608:
	v_readlane_b32 s20, v255, 41
	v_readlane_b32 s21, v255, 42
	v_readlane_b32 s22, v255, 43
	v_readlane_b32 s23, v255, 44
	s_waitcnt vmcnt(63) expcnt(7) lgkmcnt(15)
	s_waitcnt vmcnt(0)
	s_barrier
	s_mov_b64 s[2:3], exec
	v_readlane_b32 s4, v254, 0
	v_readlane_b32 s5, v254, 1
	s_and_b64 s[4:5], s[2:3], s[4:5]
	s_mov_b64 exec, s[4:5]
	s_cbranch_execnz .LBB0_1609
	s_getpc_b64 s[98:99]
